# diff-attn: exit test reads previous step flags inside PV MFMA shadow, next-step K fragment reads right after the barrier, LDS-DMA issue moved behind first two QK MFMAs
# baseline (speedup 1.0000x reference)
; __device__ __forceinline__ float bf_lo(unsigned w) { return __uint_as_float(w << 16); }
; __device__ __forceinline__ float bf_hi(unsigned w) { return __uint_as_float(w & 0xffff0000u); }
; #define WAITV_BAR(N) asm volatile("s_waitcnt vmcnt(" #N ") lgkmcnt(0)\n\ts_barrier" ::: "memory")
; #define DMA_K(ti, slot) do { int kk_ = kt_top - (ti); kk_ = kk_ < 0 ? 0 : kk_; glds16(kgb + (size_t)kk_ * (64 * NIN * 2), koff, (unsigned)__builtin_amdgcn_readfirstlane(kdst + (slot) * 8192)); } while (0)
; __device__ __forceinline__ void diff_unit(LAS unsigned char* lds, const bf16_t* __restrict__ u, bf16_t* __restrict__ yz, float* __restrict__ oscr, const unsigned* __restrict__ kb, int b, int h, int qb, float lam, float slope2, const float* __restrict__ gsub, float out_scale) {
;     ...
;         const char* kgb = (const char*)(u + rowbase * NIN + DM + (2 * h + n) * 64);
;     ...
;         DMA_K(0, 0); DMA_V(0, 0); DMA_K(1, 1); DMA_V(1, 1); DMA_K(2, 2); DMA_V(0, 3);
;         bf16x8 qf[4];
;         { int tq = threadIdx.x; asm volatile("" : "+v"(tq));
;           const bf16_t* qp = u + (rowbase + tw + (tq & 31)) * NIN + (2 * h + n) * 64 + ((tq >> 5) & 1) * 8;
; #pragma unroll
;           for (int d0 = 0; d0 < 4; ++d0) qf[d0] = *(const bf16x8*)(qp + 16 * d0); }
;         float qbound;
;         { float qs = 0.f;
; #pragma unroll
;           for (int d0 = 0; d0 < 4; ++d0) { const u32x4 w = __builtin_bit_cast(u32x4, qf[d0]);
;               const float a0 = bf_lo(w.x), a1 = bf_hi(w.x), a2 = bf_lo(w.y), a3 = bf_hi(w.y), a4 = bf_lo(w.z), a5 = bf_hi(w.z), a6 = bf_lo(w.w), a7 = bf_hi(w.w);
;               qs += (a0 * a0 + a1 * a1) + (a2 * a2 + a3 * a3) + (a4 * a4 + a5 * a5) + (a6 * a6 + a7 * a7); }
;           qs += __shfl_xor(qs, 32);
;           const float k2 = __uint_as_float(kb[(b * 16 + 2 * h + n) * 2]) + __uint_as_float(kb[(b * 16 + 2 * h + n) * 2 + 1]);
;           qbound = sqrtf(qs * k2) * 1.02f + 1.0f; }
;         float M = 1000.0f, l = 0.f;
;         SET_M(M);
;         f32x16 zero16;
; #pragma unroll
;         for (int r = 0; r < 16; ++r) zero16[r] = 0.f;
; #pragma unroll
;         for (int c = 0; c < 4; ++c)
; #pragma unroll
;             for (int r = 0; r < 16; ++r) o[c][r] = 0.f;
;         WAITV_BAR(0);
.LBB0_220:
	s_or_b32 s3, s2, s91
	s_xor_b64 s[30:31], s[8:9], -1
	s_lshl_b32 s96, s3, 7
	s_add_u32 s3, s83, s96
	s_addc_u32 s10, s88, 0
	s_add_u32 s74, s3, 0x800
	s_addc_u32 s75, s10, 0
	s_add_u32 s8, s74, s49
	s_addc_u32 s9, s75, 0
	s_mov_b32 s11, m0
	s_mov_b32 m0, s47
	s_nop 0
	global_load_lds_dwordx4 v156, s[8:9]
	s_mov_b32 m0, s11
	s_mov_b32 s8, m0
	s_mov_b32 m0, s46
	s_nop 0
	global_load_lds_dwordx4 v154, s[24:25]
	s_mov_b32 m0, s8
	s_add_i32 s76, s46, 0x2000
	s_mov_b32 s8, m0
	s_mov_b32 m0, s76
	s_nop 0
	global_load_lds_dwordx4 v155, s[24:25]
	s_mov_b32 m0, s8
	s_add_u32 s8, s74, s50
	s_addc_u32 s9, s75, 0
	s_mov_b32 s11, m0
	s_mov_b32 m0, s51
	s_nop 0
	global_load_lds_dwordx4 v156, s[8:9]
	s_mov_b32 m0, s11
	s_add_i32 s77, s52, 0x2000
	s_mov_b32 s8, m0
	s_mov_b32 m0, s52
	s_nop 0
	global_load_lds_dwordx4 v154, s[44:45]
	s_mov_b32 m0, s8
	s_add_u32 s3, s3, s33
	s_mov_b32 s8, m0
	s_mov_b32 m0, s77
	s_nop 0
	global_load_lds_dwordx4 v155, s[44:45]
	s_mov_b32 m0, s8
	s_addc_u32 s9, s10, 0
	s_add_u32 s8, s3, 0x80800
	s_addc_u32 s9, s9, 0
	s_mov_b32 s3, m0
	s_mov_b32 m0, s53
	s_nop 0
	global_load_lds_dwordx4 v156, s[8:9]
	s_mov_b32 m0, s3
	v_mov_b32_e32 v0, v140
	s_mov_b32 s3, m0
	s_mov_b32 m0, s54
	s_nop 0
	global_load_lds_dwordx4 v154, s[24:25]
	s_mov_b32 m0, s3
	s_add_i32 s78, s54, 0x2000
	s_mov_b32 s3, m0
	s_mov_b32 m0, s78
	s_nop 0
	global_load_lds_dwordx4 v155, s[24:25]
	s_mov_b32 m0, s3
	v_mov_b32_e32 v3, s56
	v_and_or_b32 v2, v0, 31, s55
	v_lshlrev_b64 v[2:3], 13, v[2:3]
	v_lshl_add_u64 v[2:3], s[34:35], 0, v[2:3]
	v_lshrrev_b32_e32 v0, 1, v0
	v_lshl_add_u64 v[2:3], v[2:3], 0, s[96:97]
	v_and_b32_e32 v0, 16, v0
	v_lshl_add_u64 v[2:3], v[2:3], 0, v[0:1]
	global_load_dwordx4 v[98:101], v[2:3], off
	global_load_dwordx4 v[102:105], v[2:3], off offset:32
	global_load_dwordx4 v[106:109], v[2:3], off offset:64
	global_load_dwordx4 v[110:113], v[2:3], off offset:96
	s_or_b32 s2, s2, s57
	s_lshl_b32 s96, s2, 1
	s_lshl_b64 s[2:3], s[96:97], 2
	s_add_u32 s2, s20, s2
	s_addc_u32 s3, s21, s3
	global_load_dwordx2 v[2:3], v1, s[2:3]
	s_mov_b32 s2, 0x3f828f5c
	v_mov_b32_e32 v238, 0
	v_mov_b32_e32 v239, s58
	ds_write_b32 v239, v238 offset:32
	s_waitcnt vmcnt(0) lgkmcnt(0)
	s_barrier
	v_mov_b64_e32 v[114:115], v[136:137]
	v_mov_b32_e32 v120, 0x447a0000
	s_mov_b32 s79, -4
	s_movk_i32 s99, 0xff00
	s_mov_b32 s48, s33
	s_mov_b32 s27, 0
	v_mov_b64_e32 v[116:117], v[138:139]
	s_waitcnt vmcnt(4)
	v_and_b32_e32 v4, 0xffff0000, v98
	v_and_b32_e32 v6, 0xffff0000, v99
	s_waitcnt vmcnt(3)
	v_and_b32_e32 v12, 0xffff0000, v102
	v_and_b32_e32 v14, 0xffff0000, v103
	v_lshlrev_b32_e32 v0, 16, v98
	v_lshlrev_b32_e32 v5, 16, v99
	v_and_b32_e32 v8, 0xffff0000, v100
	v_lshlrev_b32_e32 v11, 16, v102
	v_lshlrev_b32_e32 v13, 16, v103
	v_and_b32_e32 v16, 0xffff0000, v104
	s_waitcnt vmcnt(2)
	v_and_b32_e32 v20, 0xffff0000, v106
	v_and_b32_e32 v22, 0xffff0000, v107
	v_mul_f32_e32 v4, v4, v4
	v_mul_f32_e32 v6, v6, v6
	v_mul_f32_e32 v12, v12, v12
	v_mul_f32_e32 v14, v14, v14
	v_lshlrev_b32_e32 v7, 16, v100
	v_and_b32_e32 v10, 0xffff0000, v101
	v_lshlrev_b32_e32 v15, 16, v104
	v_and_b32_e32 v18, 0xffff0000, v105
	v_lshlrev_b32_e32 v19, 16, v106
	v_lshlrev_b32_e32 v21, 16, v107
	v_and_b32_e32 v24, 0xffff0000, v108
	v_mul_f32_e32 v8, v8, v8
	v_mul_f32_e32 v16, v16, v16
	v_mul_f32_e32 v20, v20, v20
	v_mul_f32_e32 v22, v22, v22
	v_fmac_f32_e32 v4, v0, v0
	v_fmac_f32_e32 v6, v5, v5
	v_fmac_f32_e32 v12, v11, v11
	v_fmac_f32_e32 v14, v13, v13
	v_lshlrev_b32_e32 v9, 16, v101
	v_lshlrev_b32_e32 v17, 16, v105
	v_lshlrev_b32_e32 v23, 16, v108
	v_and_b32_e32 v26, 0xffff0000, v109
	v_mul_f32_e32 v10, v10, v10
	v_mul_f32_e32 v18, v18, v18
	v_mul_f32_e32 v24, v24, v24
	v_fmac_f32_e32 v8, v7, v7
	v_fmac_f32_e32 v16, v15, v15
	v_fmac_f32_e32 v20, v19, v19
	v_fmac_f32_e32 v22, v21, v21
	v_add_f32_e32 v0, v4, v6
	v_add_f32_e32 v4, v12, v14
	v_lshlrev_b32_e32 v25, 16, v109
	v_mul_f32_e32 v26, v26, v26
	v_fmac_f32_e32 v10, v9, v9
	v_fmac_f32_e32 v18, v17, v17
	v_fmac_f32_e32 v24, v23, v23
	v_add_f32_e32 v5, v20, v22
	v_add_f32_e32 v0, v8, v0
	v_add_f32_e32 v4, v16, v4
	v_fmac_f32_e32 v26, v25, v25
	v_add_f32_e32 v5, v24, v5
	v_add_f32_e32 v0, v10, v0
	v_add_f32_e32 v4, v18, v4
	s_waitcnt vmcnt(1)
	v_and_b32_e32 v28, 0xffff0000, v110
	v_and_b32_e32 v30, 0xffff0000, v111
	v_add_f32_e32 v5, v26, v5
	v_add_f32_e32 v0, v0, v4
	v_lshlrev_b32_e32 v27, 16, v110
	v_lshlrev_b32_e32 v29, 16, v111
	v_add_f32_e32 v0, v0, v5
	v_and_b32_e32 v5, 0xffff0000, v112
	v_mul_f32_e32 v8, v28, v28
	v_mul_f32_e32 v9, v30, v30
	v_lshlrev_b32_e32 v4, 16, v112
	v_fmac_f32_e32 v8, v27, v27
	v_fmac_f32_e32 v9, v29, v29
	v_mul_f32_e32 v5, v5, v5
	v_and_b32_e32 v7, 0xffff0000, v113
	v_add_f32_e32 v8, v8, v9
	v_fmac_f32_e32 v5, v4, v4
	v_lshlrev_b32_e32 v6, 16, v113
	v_add_f32_e32 v4, v5, v8
	v_mul_f32_e32 v5, v7, v7
	v_fmac_f32_e32 v5, v6, v6
	v_add_f32_e32 v4, v5, v4
	v_add_f32_e32 v0, v0, v4
	ds_bpermute_b32 v4, v143, v0
	s_waitcnt vmcnt(0)
	v_add_f32_e32 v2, v2, v3
	s_waitcnt lgkmcnt(0)
; #define WAITV_BAR(N) asm volatile("s_waitcnt vmcnt(" #N ") lgkmcnt(0)\n\ts_barrier" ::: "memory")
; #define SET_M(Mv) do { const float m0_ = -(Mv); const unsigned h0_ = f2bf_bits(m0_); const float r1_ = m0_ - __uint_as_float(h0_ << 16); const unsigned h1_ = f2bf_bits(r1_); \
;         const float r2_ = r1_ - __uint_as_float(h1_ << 16); const unsigned h2_ = f2bf_bits(r2_); qaug = __builtin_bit_cast(bf16x8, (u32x4){qa0, qa1, hi ? 0u : (h0_ | (h1_ << 16)), hi ? 0u : h2_}); } while (0)
; __device__ __forceinline__ void diff_unit(LAS unsigned char* lds, const bf16_t* __restrict__ u, bf16_t* __restrict__ yz, float* __restrict__ oscr, const unsigned* __restrict__ kb, int b, int h, int qb, float lam, float slope2, const float* __restrict__ gsub, float out_scale) {
;     ...
;           qbound = sqrtf(qs * k2) * 1.02f + 1.0f; }
;         float M = 1000.0f, l = 0.f;
;         SET_M(M);
;         f32x16 zero16;
; #pragma unroll
;         for (int r = 0; r < 16; ++r) zero16[r] = 0.f;
; #pragma unroll
;         for (int c = 0; c < 4; ++c)
; #pragma unroll
;             for (int r = 0; r < 16; ++r) o[c][r] = 0.f;
;         WAITV_BAR(0);
	v_add_f32_e32 v0, v0, v4
	v_mul_f32_e32 v0, v2, v0
	v_mul_f32_e32 v2, 0x4f800000, v0
	v_cmp_gt_f32_e32 vcc, s93, v0
	s_nop 1
	v_cndmask_b32_e32 v0, v0, v2, vcc
	v_sqrt_f32_e32 v2, v0
	s_nop 0
	v_add_u32_e32 v3, -1, v2
	v_fma_f32 v4, -v3, v2, v0
	v_cmp_ge_f32_e64 s[8:9], 0, v4
	v_add_u32_e32 v4, 1, v2
	s_nop 0
	v_cndmask_b32_e64 v3, v2, v3, s[8:9]
	v_fma_f32 v2, -v4, v2, v0
	v_cmp_lt_f32_e64 s[8:9], 0, v2
	s_nop 1
	v_cndmask_b32_e64 v2, v3, v4, s[8:9]
	v_mul_f32_e32 v3, 0x37800000, v2
	v_cndmask_b32_e32 v2, v2, v3, vcc
	v_cmp_class_f32_e32 vcc, v0, v161
	s_nop 1
	v_cndmask_b32_e32 v2, v2, v0, vcc
	v_fma_f32 v119, v2, s2, 1.0
	v_mov_b32_e32 v2, 0
	v_mov_b32_e32 v16, v2
	v_mov_b32_e32 v17, v2
	v_mov_b32_e32 v3, v2
	v_mov_b32_e32 v4, v2
	v_mov_b32_e32 v5, v2
	v_mov_b32_e32 v6, v2
	v_mov_b32_e32 v7, v2
	v_mov_b32_e32 v8, v2
	v_mov_b32_e32 v9, v2
	v_mov_b32_e32 v10, v2
	v_mov_b32_e32 v11, v2
	v_mov_b32_e32 v12, v2
	v_mov_b32_e32 v13, v2
	v_mov_b32_e32 v14, v2
	v_mov_b32_e32 v15, v2
	v_mov_b64_e32 v[32:33], v[16:17]
	v_mov_b64_e32 v[48:49], v[16:17]
	v_mov_b64_e32 v[64:65], v[16:17]
	v_mov_b32_e32 v0, 1.0
	v_mov_b64_e32 v[30:31], v[14:15]
	v_mov_b64_e32 v[28:29], v[12:13]
	v_mov_b64_e32 v[26:27], v[10:11]
	v_mov_b64_e32 v[24:25], v[8:9]
	v_mov_b64_e32 v[22:23], v[6:7]
	v_mov_b64_e32 v[20:21], v[4:5]
	v_mov_b64_e32 v[18:19], v[2:3]
	v_mov_b64_e32 v[46:47], v[14:15]
	v_mov_b64_e32 v[44:45], v[12:13]
	v_mov_b64_e32 v[42:43], v[10:11]
	v_mov_b64_e32 v[40:41], v[8:9]
	v_mov_b64_e32 v[38:39], v[6:7]
	v_mov_b64_e32 v[36:37], v[4:5]
	v_mov_b64_e32 v[34:35], v[2:3]
	v_mov_b64_e32 v[62:63], v[14:15]
	v_mov_b64_e32 v[60:61], v[12:13]
	v_mov_b64_e32 v[58:59], v[10:11]
	v_mov_b64_e32 v[56:57], v[8:9]
	v_mov_b64_e32 v[54:55], v[6:7]
	v_mov_b64_e32 v[52:53], v[4:5]
	v_mov_b64_e32 v[50:51], v[2:3]
	v_mov_b32_e32 v118, v2
	v_mov_b32_e32 v121, v2
	v_mov_b32_e32 v122, v2
	v_mov_b32_e32 v123, v2
	v_mov_b32_e32 v124, v2
	v_mov_b32_e32 v125, v2
	v_mov_b32_e32 v126, v2
	v_mov_b32_e32 v127, v2
	v_mov_b32_e32 v129, v2
	v_mov_b32_e32 v142, v2
	v_mov_b32_e32 v175, v2
	v_mov_b32_e32 v173, v2
	v_mov_b32_e32 v178, v2
	v_mov_b32_e32 v179, v2
	v_mov_b32_e32 v182, v2
	v_mov_b32_e32 v192, v2
	v_mov_b32_e32 v193, v2
	v_mov_b32_e32 v128, v2
	v_mov_b32_e32 v174, v2
	v_mov_b32_e32 v172, v2
	v_mov_b32_e32 v176, v2
	v_mov_b32_e32 v177, v2
	v_mov_b32_e32 v180, v2
	v_mov_b32_e32 v181, v2
	v_mov_b32_e32 v183, v2
	v_mov_b32_e32 v184, v2
	v_mov_b32_e32 v185, v2
	v_mov_b32_e32 v186, v2
	v_mov_b32_e32 v188, v2
	v_mov_b32_e32 v187, v2
	v_mov_b32_e32 v189, v2
	v_mov_b32_e32 v190, v2
	v_mov_b32_e32 v191, v2
	ds_read_b128 v[66:69], v168
	ds_read_b128 v[70:73], v168 offset:4096
	ds_read_b128 v[210:213], v169
	ds_read_b128 v[214:217], v169 offset:4096
	ds_read_b128 v[218:221], v170
	ds_read_b128 v[222:225], v170 offset:4096
	ds_read_b128 v[226:229], v171
	ds_read_b128 v[234:237], v171 offset:4096
.LBB0_221:
	s_cmp_gt_u32 s27, s29
	s_cbranch_scc1 .LBB0_226
	v_add_f32_e32 v230, v128, v172
	v_add_f32_e32 v231, v174, v176
	v_add_f32_e32 v230, v177, v230
	v_add_f32_e32 v231, v180, v231
	s_waitcnt lgkmcnt(7)
	v_mfma_f32_32x32x16_bf16 v[82:97], v[66:69], v[98:101], 0
	v_add_f32_e32 v230, v181, v230
	v_add_f32_e32 v231, v183, v231
	v_add_f32_e32 v230, v184, v230
	v_add_f32_e32 v231, v185, v231
	s_waitcnt lgkmcnt(6)
	v_mfma_f32_32x32x16_bf16 v[66:81], v[70:73], v[98:101], 0
	v_add_f32_e32 v230, v186, v230
	v_add_f32_e32 v231, v188, v231
	v_add_f32_e32 v230, v187, v230
	v_add_f32_e32 v231, v189, v231
	s_add_i32 s28, s29, s79
	s_add_i32 s73, s81, s79
	s_add_u32 s2, s74, s48
	s_addc_u32 s3, s75, 0
	s_add_i32 s8, s46, 0x16000
	s_mov_b32 s9, m0
	s_mov_b32 m0, s8
	s_nop 0
	global_load_lds_dwordx4 v156, s[2:3]
	s_mov_b32 m0, s9
	s_add_i32 s3, s28, 5
	s_max_i32 s96, s3, 0
	s_add_i32 s2, s46, 0x8000
	s_lshl_b64 s[8:9], s[96:97], 19
	s_add_u32 s8, s89, s8
	s_addc_u32 s9, s90, s9
	s_mov_b32 s10, m0
	s_mov_b32 m0, s2
	s_nop 0
	global_load_lds_dwordx4 v154, s[8:9]
	s_mov_b32 m0, s10
	s_add_i32 s2, s46, 0xa000
	s_mov_b32 s10, m0
	s_mov_b32 m0, s2
	s_nop 0
	global_load_lds_dwordx4 v155, s[8:9]
	s_mov_b32 m0, s10
	s_waitcnt lgkmcnt(5)
	v_mfma_f32_32x32x16_bf16 v[82:97], v[210:213], v[102:105], v[82:97]
	v_add_f32_e32 v230, v190, v230
	v_add_f32_e32 v231, v191, v231
	v_add_f32_e32 v230, v121, v230
	v_add_f32_e32 v231, v122, v231
	s_waitcnt lgkmcnt(4)
	v_mfma_f32_32x32x16_bf16 v[66:81], v[214:217], v[102:105], v[66:81]
	v_add_f32_e32 v230, v123, v230
	v_add_f32_e32 v231, v124, v231
	v_add_f32_e32 v230, v125, v230
	v_add_f32_e32 v231, v126, v231
	s_waitcnt lgkmcnt(3)
	v_mfma_f32_32x32x16_bf16 v[82:97], v[218:221], v[106:109], v[82:97]
	v_add_f32_e32 v230, v127, v230
	v_add_f32_e32 v231, v129, v231
	v_add_f32_e32 v230, v142, v230
	v_add_f32_e32 v231, v175, v231
	s_waitcnt lgkmcnt(2)
	v_mfma_f32_32x32x16_bf16 v[66:81], v[222:225], v[106:109], v[66:81]
	v_add_f32_e32 v230, v173, v230
	v_add_f32_e32 v231, v178, v231
	v_add_f32_e32 v230, v179, v230
	v_add_f32_e32 v231, v182, v231
	s_waitcnt lgkmcnt(1)
	v_mfma_f32_32x32x16_bf16 v[82:97], v[226:229], v[110:113], v[82:97]
	v_add_f32_e32 v230, v192, v230
	v_add_f32_e32 v231, v193, v231
	v_add_f32_e32 v230, v230, v231
	v_add_f32_e32 v118, v118, v230
	s_waitcnt lgkmcnt(0)
	v_mfma_f32_32x32x16_bf16 v[66:81], v[234:237], v[110:113], v[66:81]
	s_add_i32 s2, s79, 3
	v_cvt_f32_i32_e32 v238, s2
	v_or_b32_sdwa v132, v238, v157 dst_sel:DWORD dst_unused:UNUSED_PAD src0_sel:WORD_1 src1_sel:DWORD
	v_or_b32_sdwa v133, v238, v157 dst_sel:DWORD dst_unused:UNUSED_PAD src0_sel:WORD_1 src1_sel:DWORD
	ds_read_b64_tr_b16 v[210:211], v146 offset:49152
	ds_read_b64_tr_b16 v[212:213], v147 offset:49152
	ds_read_b64_tr_b16 v[214:215], v148 offset:49152
	ds_read_b64_tr_b16 v[216:217], v149 offset:49152
	v_mfma_f32_32x32x16_bf16 v[82:97], v[132:135], v[114:117], v[82:97]
	v_or_b32_sdwa v132, v238, v158 dst_sel:DWORD dst_unused:UNUSED_PAD src0_sel:WORD_1 src1_sel:DWORD
	v_or_b32_sdwa v133, v238, v158 dst_sel:DWORD dst_unused:UNUSED_PAD src0_sel:WORD_1 src1_sel:DWORD
	ds_read_b64_tr_b16 v[218:219], v150 offset:49152
	ds_read_b64_tr_b16 v[220:221], v151 offset:49152
	ds_read_b64_tr_b16 v[222:223], v152 offset:49152
	ds_read_b64_tr_b16 v[224:225], v153 offset:49152
	v_mfma_f32_32x32x16_bf16 v[66:81], v[132:135], v[114:117], v[66:81]
	ds_read_b64_tr_b16 v[226:227], v146 offset:53248
	ds_read_b64_tr_b16 v[228:229], v147 offset:53248
	ds_read_b64_tr_b16 v[234:235], v148 offset:53248
	ds_read_b64_tr_b16 v[236:237], v149 offset:53248
	v_cvt_pk_bf16_f32 v194, v128, v174
	v_cvt_pk_bf16_f32 v195, v172, v176
	v_cvt_pk_bf16_f32 v196, v177, v180
	v_cvt_pk_bf16_f32 v197, v181, v183
	v_cvt_pk_bf16_f32 v198, v184, v185
	v_cvt_pk_bf16_f32 v199, v186, v188
	v_cvt_pk_bf16_f32 v200, v187, v189
	v_cvt_pk_bf16_f32 v201, v190, v191
	v_cvt_pk_bf16_f32 v202, v121, v122
	v_cvt_pk_bf16_f32 v203, v123, v124
	v_cvt_pk_bf16_f32 v204, v125, v126
	v_cvt_pk_bf16_f32 v205, v127, v129
	v_cvt_pk_bf16_f32 v206, v142, v175
	v_cvt_pk_bf16_f32 v207, v173, v178
	v_cvt_pk_bf16_f32 v208, v179, v182
	v_cvt_pk_bf16_f32 v209, v192, v193
	s_cmp_lg_u32 s73, -7
	s_cselect_b64 s[8:9], -1, 0
	s_cmp_eq_u32 s73, -7
	s_cselect_b64 s[12:13], -1, 0
	s_and_b64 vcc, exec, s[8:9]
	s_cbranch_vccnz .LBB0_224
	v_sub_f32_e32 v230, 0, v159
	v_sub_f32_e32 v231, 0x3f800000, v159
	v_max_f32_e32 v230, 0, v230
	v_max_f32_e32 v231, 0, v231
	v_pk_fma_f32 v[82:83], s[16:17], v[230:231], v[82:83] neg_lo:[1,0,0] neg_hi:[1,0,0]
	v_sub_f32_e32 v238, 0x40000000, v159
	v_sub_f32_e32 v239, 0x40400000, v159
	v_max_f32_e32 v238, 0, v238
	v_max_f32_e32 v239, 0, v239
	v_pk_fma_f32 v[84:85], s[16:17], v[238:239], v[84:85] neg_lo:[1,0,0] neg_hi:[1,0,0]
	v_sub_f32_e32 v230, 0x40800000, v159
	v_sub_f32_e32 v231, 0x40a00000, v159
	v_max_f32_e32 v230, 0, v230
	v_max_f32_e32 v231, 0, v231
	v_pk_fma_f32 v[86:87], s[16:17], v[230:231], v[86:87] neg_lo:[1,0,0] neg_hi:[1,0,0]
	v_sub_f32_e32 v238, 0x40c00000, v159
	v_sub_f32_e32 v239, 0x40e00000, v159
	v_max_f32_e32 v238, 0, v238
	v_max_f32_e32 v239, 0, v239
	v_pk_fma_f32 v[88:89], s[16:17], v[238:239], v[88:89] neg_lo:[1,0,0] neg_hi:[1,0,0]
	v_sub_f32_e32 v230, 0x41800000, v159
	v_sub_f32_e32 v231, 0x41880000, v159
	v_max_f32_e32 v230, 0, v230
	v_max_f32_e32 v231, 0, v231
	v_pk_fma_f32 v[90:91], s[16:17], v[230:231], v[90:91] neg_lo:[1,0,0] neg_hi:[1,0,0]
	v_sub_f32_e32 v238, 0x41900000, v159
	v_sub_f32_e32 v239, 0x41980000, v159
	v_max_f32_e32 v238, 0, v238
	v_max_f32_e32 v239, 0, v239
	v_pk_fma_f32 v[92:93], s[16:17], v[238:239], v[92:93] neg_lo:[1,0,0] neg_hi:[1,0,0]
	v_sub_f32_e32 v230, 0x41a00000, v159
	v_sub_f32_e32 v231, 0x41a80000, v159
	v_max_f32_e32 v230, 0, v230
	v_max_f32_e32 v231, 0, v231
	v_pk_fma_f32 v[94:95], s[16:17], v[230:231], v[94:95] neg_lo:[1,0,0] neg_hi:[1,0,0]
	v_sub_f32_e32 v238, 0x41b00000, v159
	v_sub_f32_e32 v239, 0x41b80000, v159
	v_max_f32_e32 v238, 0, v238
	v_max_f32_e32 v239, 0, v239
	v_pk_fma_f32 v[96:97], s[16:17], v[238:239], v[96:97] neg_lo:[1,0,0] neg_hi:[1,0,0]
	v_sub_f32_e32 v230, 0x42000000, v159
	v_sub_f32_e32 v231, 0x42040000, v159
	v_max_f32_e32 v230, 0, v230
	v_max_f32_e32 v231, 0, v231
	v_pk_fma_f32 v[66:67], s[16:17], v[230:231], v[66:67] neg_lo:[1,0,0] neg_hi:[1,0,0]
	v_sub_f32_e32 v238, 0x42080000, v159
	v_sub_f32_e32 v239, 0x420c0000, v159
	v_max_f32_e32 v238, 0, v238
	v_max_f32_e32 v239, 0, v239
	v_pk_fma_f32 v[68:69], s[16:17], v[238:239], v[68:69] neg_lo:[1,0,0] neg_hi:[1,0,0]
	v_sub_f32_e32 v230, 0x42100000, v159
	v_sub_f32_e32 v231, 0x42140000, v159
	v_max_f32_e32 v230, 0, v230
	v_max_f32_e32 v231, 0, v231
	v_pk_fma_f32 v[70:71], s[16:17], v[230:231], v[70:71] neg_lo:[1,0,0] neg_hi:[1,0,0]
	v_sub_f32_e32 v238, 0x42180000, v159
	v_sub_f32_e32 v239, 0x421c0000, v159
	v_max_f32_e32 v238, 0, v238
	v_max_f32_e32 v239, 0, v239
	v_pk_fma_f32 v[72:73], s[16:17], v[238:239], v[72:73] neg_lo:[1,0,0] neg_hi:[1,0,0]
	v_sub_f32_e32 v230, 0x42400000, v159
	v_sub_f32_e32 v231, 0x42440000, v159
	v_max_f32_e32 v230, 0, v230
	v_max_f32_e32 v231, 0, v231
	v_pk_fma_f32 v[74:75], s[16:17], v[230:231], v[74:75] neg_lo:[1,0,0] neg_hi:[1,0,0]
	v_sub_f32_e32 v238, 0x42480000, v159
	v_sub_f32_e32 v239, 0x424c0000, v159
	v_max_f32_e32 v238, 0, v238
	v_max_f32_e32 v239, 0, v239
	v_pk_fma_f32 v[76:77], s[16:17], v[238:239], v[76:77] neg_lo:[1,0,0] neg_hi:[1,0,0]
	v_sub_f32_e32 v230, 0x42500000, v159
	v_sub_f32_e32 v231, 0x42540000, v159
	v_max_f32_e32 v230, 0, v230
	v_max_f32_e32 v231, 0, v231
	v_pk_fma_f32 v[78:79], s[16:17], v[230:231], v[78:79] neg_lo:[1,0,0] neg_hi:[1,0,0]
	v_sub_f32_e32 v238, 0x42580000, v159
	v_sub_f32_e32 v239, 0x425c0000, v159
	v_max_f32_e32 v238, 0, v238
	v_max_f32_e32 v239, 0, v239
	v_pk_fma_f32 v[80:81], s[16:17], v[238:239], v[80:81] neg_lo:[1,0,0] neg_hi:[1,0,0]

.LBB0_231:
	s_waitcnt lgkmcnt(10)
	v_mfma_f32_32x32x16_bf16 v[2:17], v[210:213], v[194:197], v[2:17]
	ds_read_b64_tr_b16 v[210:211], v150 offset:53248
	ds_read_b64_tr_b16 v[212:213], v151 offset:53248
	v_exp_f32_e32 v121, v66
	v_exp_f32_e32 v122, v67
	s_waitcnt lgkmcnt(10)
	v_mfma_f32_32x32x16_bf16 v[18:33], v[214:217], v[194:197], v[18:33]
	ds_read_b64_tr_b16 v[214:215], v152 offset:53248
	ds_read_b64_tr_b16 v[216:217], v153 offset:53248
	v_exp_f32_e32 v123, v68
	v_exp_f32_e32 v124, v69
	s_waitcnt lgkmcnt(10)
	v_mfma_f32_32x32x16_bf16 v[34:49], v[218:221], v[194:197], v[34:49]
	ds_read_b64_tr_b16 v[218:219], v146 offset:57344
	ds_read_b64_tr_b16 v[220:221], v147 offset:57344
	v_exp_f32_e32 v125, v70
	v_exp_f32_e32 v126, v71
	s_waitcnt lgkmcnt(10)
	v_mfma_f32_32x32x16_bf16 v[50:65], v[222:225], v[194:197], v[50:65]
	ds_read_b64_tr_b16 v[222:223], v148 offset:57344
	ds_read_b64_tr_b16 v[224:225], v149 offset:57344
	v_exp_f32_e32 v127, v72
	v_exp_f32_e32 v129, v73
	v_mov_b32_e32 v238, 0x18020
	ds_read_b128 v[66:69], v238
	v_mov_b32_e32 v239, 0x18030
	ds_read_b128 v[70:73], v239
	s_waitcnt lgkmcnt(12)
	v_mfma_f32_32x32x16_bf16 v[2:17], v[226:229], v[198:201], v[2:17]
	ds_read_b64_tr_b16 v[226:227], v150 offset:57344
	ds_read_b64_tr_b16 v[228:229], v151 offset:57344
	v_exp_f32_e32 v128, v82
	v_exp_f32_e32 v174, v83
	s_waitcnt lgkmcnt(12)
	v_mfma_f32_32x32x16_bf16 v[18:33], v[234:237], v[198:201], v[18:33]
	ds_read_b64_tr_b16 v[234:235], v152 offset:57344
	ds_read_b64_tr_b16 v[236:237], v153 offset:57344
	v_exp_f32_e32 v172, v84
	v_exp_f32_e32 v176, v85
	s_waitcnt lgkmcnt(12)
	v_mfma_f32_32x32x16_bf16 v[34:49], v[210:213], v[198:201], v[34:49]
	ds_read_b64_tr_b16 v[210:211], v146 offset:61440
	ds_read_b64_tr_b16 v[212:213], v147 offset:61440
	v_exp_f32_e32 v177, v86
	v_exp_f32_e32 v180, v87
	s_waitcnt lgkmcnt(12)
	v_mfma_f32_32x32x16_bf16 v[50:65], v[214:217], v[198:201], v[50:65]
	ds_read_b64_tr_b16 v[214:215], v148 offset:61440
	ds_read_b64_tr_b16 v[216:217], v149 offset:61440
	v_exp_f32_e32 v181, v88
	v_exp_f32_e32 v183, v89
	s_waitcnt lgkmcnt(12)
	v_mfma_f32_32x32x16_bf16 v[2:17], v[218:221], v[202:205], v[2:17]
	ds_read_b64_tr_b16 v[218:219], v150 offset:61440
	ds_read_b64_tr_b16 v[220:221], v151 offset:61440
	v_exp_f32_e32 v184, v90
	v_exp_f32_e32 v185, v91
	s_waitcnt lgkmcnt(12)
	v_mfma_f32_32x32x16_bf16 v[18:33], v[222:225], v[202:205], v[18:33]
	ds_read_b64_tr_b16 v[222:223], v152 offset:61440
	ds_read_b64_tr_b16 v[224:225], v153 offset:61440
	v_exp_f32_e32 v186, v92
	v_exp_f32_e32 v188, v93
	s_waitcnt lgkmcnt(10)
	v_mfma_f32_32x32x16_bf16 v[34:49], v[226:229], v[202:205], v[34:49]
	v_exp_f32_e32 v187, v94
	v_exp_f32_e32 v189, v95
	s_waitcnt lgkmcnt(8)
	v_mfma_f32_32x32x16_bf16 v[50:65], v[234:237], v[202:205], v[50:65]
	v_exp_f32_e32 v190, v96
	v_exp_f32_e32 v191, v97
	s_waitcnt lgkmcnt(6)
	v_mfma_f32_32x32x16_bf16 v[2:17], v[210:213], v[206:209], v[2:17]
	v_exp_f32_e32 v142, v74
	v_exp_f32_e32 v175, v75
	v_and_b32_e32 v66, v66, v67
	v_and_b32_e32 v68, v68, v69
	s_waitcnt lgkmcnt(4)
	v_mfma_f32_32x32x16_bf16 v[18:33], v[214:217], v[206:209], v[18:33]
	v_exp_f32_e32 v173, v76
	v_exp_f32_e32 v178, v77
	v_and_b32_e32 v70, v70, v71
	v_and_b32_e32 v72, v72, v73
	s_waitcnt lgkmcnt(2)
	v_mfma_f32_32x32x16_bf16 v[34:49], v[218:221], v[206:209], v[34:49]
	v_exp_f32_e32 v179, v78
	v_exp_f32_e32 v182, v79
	v_and_b32_e32 v66, v66, v68
	v_and_b32_e32 v70, v70, v72
	s_waitcnt lgkmcnt(0)
	v_mfma_f32_32x32x16_bf16 v[50:65], v[222:225], v[206:209], v[50:65]
	v_exp_f32_e32 v192, v80
	v_exp_f32_e32 v193, v81
	v_and_b32_e32 v66, v66, v70
	s_andn2_b64 vcc, exec, s[12:13]
	s_cbranch_vccz .LBB0_240
	s_add_i32 s2, s28, 7
	s_cmp_gt_i32 s2, s82
	v_mov_b32_e32 v238, 0
	s_cbranch_scc0 .LBB0_241

.LBB0_235:
	s_or_b64 exec, exec, s[8:9]
	s_add_i32 s2, 0, 0x18000
	s_waitcnt vmcnt(6) lgkmcnt(0)
	s_barrier
	v_cmp_ne_u32_e32 vcc, 0, v66
	ds_read_b128 v[66:69], v168 offset:8192
	ds_read_b128 v[70:73], v168 offset:12288
	ds_read_b128 v[210:213], v169 offset:8192
	ds_read_b128 v[214:217], v169 offset:12288
	ds_read_b128 v[218:221], v170 offset:8192
	ds_read_b128 v[222:225], v170 offset:12288
	ds_read_b128 v[226:229], v171 offset:8192
	ds_read_b128 v[234:237], v171 offset:12288
	s_mov_b64 s[8:9], -1
	s_mov_b32 s10, 0
	s_cbranch_vccnz .LBB0_268
	v_add_f32_e32 v230, v128, v172
	v_add_f32_e32 v231, v174, v176
	v_add_f32_e32 v230, v177, v230
	v_add_f32_e32 v231, v180, v231
	s_waitcnt lgkmcnt(7)
	v_mfma_f32_32x32x16_bf16 v[82:97], v[66:69], v[98:101], 0
	v_add_f32_e32 v230, v181, v230
	v_add_f32_e32 v231, v183, v231
	v_add_f32_e32 v230, v184, v230
	v_add_f32_e32 v231, v185, v231
	s_waitcnt lgkmcnt(6)
	v_mfma_f32_32x32x16_bf16 v[66:81], v[70:73], v[98:101], 0
	v_add_f32_e32 v230, v186, v230
	v_add_f32_e32 v231, v188, v231
	v_add_f32_e32 v230, v187, v230
	v_add_f32_e32 v231, v189, v231
	s_add_i32 s8, s28, 3
	s_max_i32 s96, s8, 0
	s_lshl_b64 s[8:9], s[96:97], 19
	s_add_u32 s10, s74, s8
	s_addc_u32 s11, s75, s9
	s_mov_b32 s12, m0
	s_mov_b32 m0, s47
	s_nop 0
	global_load_lds_dwordx4 v156, s[10:11]
	s_mov_b32 m0, s12
	s_add_u32 s10, s89, s48
	s_addc_u32 s11, s90, 0
	s_mov_b32 s12, m0
	s_mov_b32 m0, s54
	s_nop 0
	global_load_lds_dwordx4 v154, s[10:11]
	s_mov_b32 m0, s12
	s_nop 0
	s_mov_b32 s12, m0
	s_mov_b32 m0, s78
	s_nop 0
	global_load_lds_dwordx4 v155, s[10:11]
	s_mov_b32 m0, s12
	s_waitcnt lgkmcnt(5)
	v_mfma_f32_32x32x16_bf16 v[82:97], v[210:213], v[102:105], v[82:97]
	v_add_f32_e32 v230, v190, v230
	v_add_f32_e32 v231, v191, v231
	v_add_f32_e32 v230, v121, v230
	v_add_f32_e32 v231, v122, v231
	s_waitcnt lgkmcnt(4)
	v_mfma_f32_32x32x16_bf16 v[66:81], v[214:217], v[102:105], v[66:81]
	v_add_f32_e32 v230, v123, v230
	v_add_f32_e32 v231, v124, v231
	v_add_f32_e32 v230, v125, v230
	v_add_f32_e32 v231, v126, v231
	s_waitcnt lgkmcnt(3)
	v_mfma_f32_32x32x16_bf16 v[82:97], v[218:221], v[106:109], v[82:97]
	v_add_f32_e32 v230, v127, v230
	v_add_f32_e32 v231, v129, v231
	v_add_f32_e32 v230, v142, v230
	v_add_f32_e32 v231, v175, v231
	s_waitcnt lgkmcnt(2)
	v_mfma_f32_32x32x16_bf16 v[66:81], v[222:225], v[106:109], v[66:81]
	v_add_f32_e32 v230, v173, v230
	v_add_f32_e32 v231, v178, v231
	v_add_f32_e32 v230, v179, v230
	v_add_f32_e32 v231, v182, v231
	s_waitcnt lgkmcnt(1)
	v_mfma_f32_32x32x16_bf16 v[82:97], v[226:229], v[110:113], v[82:97]
	v_add_f32_e32 v230, v192, v230
	v_add_f32_e32 v231, v193, v231
	v_add_f32_e32 v230, v230, v231
	v_add_f32_e32 v118, v118, v230
	s_waitcnt lgkmcnt(0)
	v_mfma_f32_32x32x16_bf16 v[66:81], v[234:237], v[110:113], v[66:81]
	s_add_i32 s10, s79, 2
	v_cvt_f32_i32_e32 v238, s10
	v_or_b32_sdwa v132, v238, v157 dst_sel:DWORD dst_unused:UNUSED_PAD src0_sel:WORD_1 src1_sel:DWORD
	v_or_b32_sdwa v133, v238, v157 dst_sel:DWORD dst_unused:UNUSED_PAD src0_sel:WORD_1 src1_sel:DWORD
	ds_read_b64_tr_b16 v[210:211], v146
	ds_read_b64_tr_b16 v[212:213], v147
	ds_read_b64_tr_b16 v[214:215], v148
	ds_read_b64_tr_b16 v[216:217], v149
	v_mfma_f32_32x32x16_bf16 v[82:97], v[132:135], v[114:117], v[82:97]
	v_or_b32_sdwa v132, v238, v158 dst_sel:DWORD dst_unused:UNUSED_PAD src0_sel:WORD_1 src1_sel:DWORD
	v_or_b32_sdwa v133, v238, v158 dst_sel:DWORD dst_unused:UNUSED_PAD src0_sel:WORD_1 src1_sel:DWORD
	ds_read_b64_tr_b16 v[218:219], v150
	ds_read_b64_tr_b16 v[220:221], v151
	ds_read_b64_tr_b16 v[222:223], v152
	ds_read_b64_tr_b16 v[224:225], v153
	v_mfma_f32_32x32x16_bf16 v[66:81], v[132:135], v[114:117], v[66:81]
	ds_read_b64_tr_b16 v[226:227], v146 offset:4096
	ds_read_b64_tr_b16 v[228:229], v147 offset:4096
	ds_read_b64_tr_b16 v[234:235], v148 offset:4096
	ds_read_b64_tr_b16 v[236:237], v149 offset:4096
	v_cvt_pk_bf16_f32 v194, v128, v174
	v_cvt_pk_bf16_f32 v195, v172, v176
	v_cvt_pk_bf16_f32 v196, v177, v180
	v_cvt_pk_bf16_f32 v197, v181, v183
	v_cvt_pk_bf16_f32 v198, v184, v185
	v_cvt_pk_bf16_f32 v199, v186, v188
	v_cvt_pk_bf16_f32 v200, v187, v189
	v_cvt_pk_bf16_f32 v201, v190, v191
	v_cvt_pk_bf16_f32 v202, v121, v122
	v_cvt_pk_bf16_f32 v203, v123, v124
	v_cvt_pk_bf16_f32 v204, v125, v126
	v_cvt_pk_bf16_f32 v205, v127, v129
	v_cvt_pk_bf16_f32 v206, v142, v175
	v_cvt_pk_bf16_f32 v207, v173, v178
	v_cvt_pk_bf16_f32 v208, v179, v182
	v_cvt_pk_bf16_f32 v209, v192, v193
	s_cmp_lg_u32 s73, -6
	s_cselect_b64 s[12:13], -1, 0
	s_cmp_eq_u32 s73, -6
	s_cselect_b64 s[14:15], -1, 0
	s_and_b64 vcc, exec, s[12:13]
	s_cbranch_vccnz .LBB0_238
	v_sub_f32_e32 v230, 0, v159
	v_sub_f32_e32 v231, 0x3f800000, v159
	v_max_f32_e32 v230, 0, v230
	v_max_f32_e32 v231, 0, v231
	v_pk_fma_f32 v[82:83], s[16:17], v[230:231], v[82:83] neg_lo:[1,0,0] neg_hi:[1,0,0]
	v_sub_f32_e32 v238, 0x40000000, v159
	v_sub_f32_e32 v239, 0x40400000, v159
	v_max_f32_e32 v238, 0, v238
	v_max_f32_e32 v239, 0, v239
	v_pk_fma_f32 v[84:85], s[16:17], v[238:239], v[84:85] neg_lo:[1,0,0] neg_hi:[1,0,0]
	v_sub_f32_e32 v230, 0x40800000, v159
	v_sub_f32_e32 v231, 0x40a00000, v159
	v_max_f32_e32 v230, 0, v230
	v_max_f32_e32 v231, 0, v231
	v_pk_fma_f32 v[86:87], s[16:17], v[230:231], v[86:87] neg_lo:[1,0,0] neg_hi:[1,0,0]
	v_sub_f32_e32 v238, 0x40c00000, v159
	v_sub_f32_e32 v239, 0x40e00000, v159
	v_max_f32_e32 v238, 0, v238
	v_max_f32_e32 v239, 0, v239
	v_pk_fma_f32 v[88:89], s[16:17], v[238:239], v[88:89] neg_lo:[1,0,0] neg_hi:[1,0,0]
	v_sub_f32_e32 v230, 0x41800000, v159
	v_sub_f32_e32 v231, 0x41880000, v159
	v_max_f32_e32 v230, 0, v230
	v_max_f32_e32 v231, 0, v231
	v_pk_fma_f32 v[90:91], s[16:17], v[230:231], v[90:91] neg_lo:[1,0,0] neg_hi:[1,0,0]
	v_sub_f32_e32 v238, 0x41900000, v159
	v_sub_f32_e32 v239, 0x41980000, v159
	v_max_f32_e32 v238, 0, v238
	v_max_f32_e32 v239, 0, v239
	v_pk_fma_f32 v[92:93], s[16:17], v[238:239], v[92:93] neg_lo:[1,0,0] neg_hi:[1,0,0]
	v_sub_f32_e32 v230, 0x41a00000, v159
	v_sub_f32_e32 v231, 0x41a80000, v159
	v_max_f32_e32 v230, 0, v230
	v_max_f32_e32 v231, 0, v231
	v_pk_fma_f32 v[94:95], s[16:17], v[230:231], v[94:95] neg_lo:[1,0,0] neg_hi:[1,0,0]
	v_sub_f32_e32 v238, 0x41b00000, v159
	v_sub_f32_e32 v239, 0x41b80000, v159
	v_max_f32_e32 v238, 0, v238
	v_max_f32_e32 v239, 0, v239
	v_pk_fma_f32 v[96:97], s[16:17], v[238:239], v[96:97] neg_lo:[1,0,0] neg_hi:[1,0,0]
	v_sub_f32_e32 v230, 0x42000000, v159
	v_sub_f32_e32 v231, 0x42040000, v159
	v_max_f32_e32 v230, 0, v230
	v_max_f32_e32 v231, 0, v231
	v_pk_fma_f32 v[66:67], s[16:17], v[230:231], v[66:67] neg_lo:[1,0,0] neg_hi:[1,0,0]
	v_sub_f32_e32 v238, 0x42080000, v159
	v_sub_f32_e32 v239, 0x420c0000, v159
	v_max_f32_e32 v238, 0, v238
	v_max_f32_e32 v239, 0, v239
	v_pk_fma_f32 v[68:69], s[16:17], v[238:239], v[68:69] neg_lo:[1,0,0] neg_hi:[1,0,0]
	v_sub_f32_e32 v230, 0x42100000, v159
	v_sub_f32_e32 v231, 0x42140000, v159
	v_max_f32_e32 v230, 0, v230
	v_max_f32_e32 v231, 0, v231
	v_pk_fma_f32 v[70:71], s[16:17], v[230:231], v[70:71] neg_lo:[1,0,0] neg_hi:[1,0,0]
	v_sub_f32_e32 v238, 0x42180000, v159
	v_sub_f32_e32 v239, 0x421c0000, v159
	v_max_f32_e32 v238, 0, v238
	v_max_f32_e32 v239, 0, v239
	v_pk_fma_f32 v[72:73], s[16:17], v[238:239], v[72:73] neg_lo:[1,0,0] neg_hi:[1,0,0]
	v_sub_f32_e32 v230, 0x42400000, v159
	v_sub_f32_e32 v231, 0x42440000, v159
	v_max_f32_e32 v230, 0, v230
	v_max_f32_e32 v231, 0, v231
	v_pk_fma_f32 v[74:75], s[16:17], v[230:231], v[74:75] neg_lo:[1,0,0] neg_hi:[1,0,0]
	v_sub_f32_e32 v238, 0x42480000, v159
	v_sub_f32_e32 v239, 0x424c0000, v159
	v_max_f32_e32 v238, 0, v238
	v_max_f32_e32 v239, 0, v239
	v_pk_fma_f32 v[76:77], s[16:17], v[238:239], v[76:77] neg_lo:[1,0,0] neg_hi:[1,0,0]
	v_sub_f32_e32 v230, 0x42500000, v159
	v_sub_f32_e32 v231, 0x42540000, v159
	v_max_f32_e32 v230, 0, v230
	v_max_f32_e32 v231, 0, v231
	v_pk_fma_f32 v[78:79], s[16:17], v[230:231], v[78:79] neg_lo:[1,0,0] neg_hi:[1,0,0]
	v_sub_f32_e32 v238, 0x42580000, v159
	v_sub_f32_e32 v239, 0x425c0000, v159
	v_max_f32_e32 v238, 0, v238
	v_max_f32_e32 v239, 0, v239
	v_pk_fma_f32 v[80:81], s[16:17], v[238:239], v[80:81] neg_lo:[1,0,0] neg_hi:[1,0,0]

.LBB0_246:
	s_waitcnt lgkmcnt(10)
	v_mfma_f32_32x32x16_bf16 v[2:17], v[210:213], v[194:197], v[2:17]
	ds_read_b64_tr_b16 v[210:211], v150 offset:4096
	ds_read_b64_tr_b16 v[212:213], v151 offset:4096
	v_exp_f32_e32 v121, v66
	v_exp_f32_e32 v122, v67
	s_waitcnt lgkmcnt(10)
	v_mfma_f32_32x32x16_bf16 v[18:33], v[214:217], v[194:197], v[18:33]
	ds_read_b64_tr_b16 v[214:215], v152 offset:4096
	ds_read_b64_tr_b16 v[216:217], v153 offset:4096
	v_exp_f32_e32 v123, v68
	v_exp_f32_e32 v124, v69
	s_waitcnt lgkmcnt(10)
	v_mfma_f32_32x32x16_bf16 v[34:49], v[218:221], v[194:197], v[34:49]
	ds_read_b64_tr_b16 v[218:219], v146 offset:8192
	ds_read_b64_tr_b16 v[220:221], v147 offset:8192
	v_exp_f32_e32 v125, v70
	v_exp_f32_e32 v126, v71
	s_waitcnt lgkmcnt(10)
	v_mfma_f32_32x32x16_bf16 v[50:65], v[222:225], v[194:197], v[50:65]
	ds_read_b64_tr_b16 v[222:223], v148 offset:8192
	ds_read_b64_tr_b16 v[224:225], v149 offset:8192
	v_exp_f32_e32 v127, v72
	v_exp_f32_e32 v129, v73
	v_mov_b32_e32 v238, 0x18000
	ds_read_b128 v[66:69], v238
	v_mov_b32_e32 v239, 0x18010
	ds_read_b128 v[70:73], v239
	s_waitcnt lgkmcnt(12)
	v_mfma_f32_32x32x16_bf16 v[2:17], v[226:229], v[198:201], v[2:17]
	ds_read_b64_tr_b16 v[226:227], v150 offset:8192
	ds_read_b64_tr_b16 v[228:229], v151 offset:8192
	v_exp_f32_e32 v128, v82
	v_exp_f32_e32 v174, v83
	s_waitcnt lgkmcnt(12)
	v_mfma_f32_32x32x16_bf16 v[18:33], v[234:237], v[198:201], v[18:33]
	ds_read_b64_tr_b16 v[234:235], v152 offset:8192
	ds_read_b64_tr_b16 v[236:237], v153 offset:8192
	v_exp_f32_e32 v172, v84
	v_exp_f32_e32 v176, v85
	s_waitcnt lgkmcnt(12)
	v_mfma_f32_32x32x16_bf16 v[34:49], v[210:213], v[198:201], v[34:49]
	ds_read_b64_tr_b16 v[210:211], v146 offset:12288
	ds_read_b64_tr_b16 v[212:213], v147 offset:12288
	v_exp_f32_e32 v177, v86
	v_exp_f32_e32 v180, v87
	s_waitcnt lgkmcnt(12)
	v_mfma_f32_32x32x16_bf16 v[50:65], v[214:217], v[198:201], v[50:65]
	ds_read_b64_tr_b16 v[214:215], v148 offset:12288
	ds_read_b64_tr_b16 v[216:217], v149 offset:12288
	v_exp_f32_e32 v181, v88
	v_exp_f32_e32 v183, v89
	s_waitcnt lgkmcnt(12)
	v_mfma_f32_32x32x16_bf16 v[2:17], v[218:221], v[202:205], v[2:17]
	ds_read_b64_tr_b16 v[218:219], v150 offset:12288
	ds_read_b64_tr_b16 v[220:221], v151 offset:12288
	v_exp_f32_e32 v184, v90
	v_exp_f32_e32 v185, v91
	s_waitcnt lgkmcnt(12)
	v_mfma_f32_32x32x16_bf16 v[18:33], v[222:225], v[202:205], v[18:33]
	ds_read_b64_tr_b16 v[222:223], v152 offset:12288
	ds_read_b64_tr_b16 v[224:225], v153 offset:12288
	v_exp_f32_e32 v186, v92
	v_exp_f32_e32 v188, v93
	s_waitcnt lgkmcnt(10)
	v_mfma_f32_32x32x16_bf16 v[34:49], v[226:229], v[202:205], v[34:49]
	v_exp_f32_e32 v187, v94
	v_exp_f32_e32 v189, v95
	s_waitcnt lgkmcnt(8)
	v_mfma_f32_32x32x16_bf16 v[50:65], v[234:237], v[202:205], v[50:65]
	v_exp_f32_e32 v190, v96
	v_exp_f32_e32 v191, v97
	s_waitcnt lgkmcnt(6)
	v_mfma_f32_32x32x16_bf16 v[2:17], v[210:213], v[206:209], v[2:17]
	v_exp_f32_e32 v142, v74
	v_exp_f32_e32 v175, v75
	v_and_b32_e32 v66, v66, v67
	v_and_b32_e32 v68, v68, v69
	s_waitcnt lgkmcnt(4)
	v_mfma_f32_32x32x16_bf16 v[18:33], v[214:217], v[206:209], v[18:33]
	v_exp_f32_e32 v173, v76
	v_exp_f32_e32 v178, v77
	v_and_b32_e32 v70, v70, v71
	v_and_b32_e32 v72, v72, v73
	s_waitcnt lgkmcnt(2)
	v_mfma_f32_32x32x16_bf16 v[34:49], v[218:221], v[206:209], v[34:49]
	v_exp_f32_e32 v179, v78
	v_exp_f32_e32 v182, v79
	v_and_b32_e32 v66, v66, v68
	v_and_b32_e32 v70, v70, v72
	s_waitcnt lgkmcnt(0)
	v_mfma_f32_32x32x16_bf16 v[50:65], v[222:225], v[206:209], v[50:65]
	v_exp_f32_e32 v192, v80
	v_exp_f32_e32 v193, v81
	v_and_b32_e32 v66, v66, v70
	s_andn2_b64 vcc, exec, s[14:15]
	s_cbranch_vccz .LBB0_252
	s_add_i32 s10, s28, 6
	s_cmp_gt_i32 s10, s82
	v_mov_b32_e32 v238, 0
	s_cbranch_scc0 .LBB0_253

.LBB0_250:
	s_or_b64 exec, exec, s[10:11]
	s_waitcnt vmcnt(6) lgkmcnt(0)
	s_barrier
	v_cmp_ne_u32_e32 vcc, 0, v66
	ds_read_b128 v[66:69], v168 offset:16384
	ds_read_b128 v[70:73], v168 offset:20480
	ds_read_b128 v[210:213], v169 offset:16384
	ds_read_b128 v[214:217], v169 offset:20480
	ds_read_b128 v[218:221], v170 offset:16384
	ds_read_b128 v[222:225], v170 offset:20480
	ds_read_b128 v[226:229], v171 offset:16384
	ds_read_b128 v[234:237], v171 offset:20480
	s_cbranch_vccz .LBB0_254
	s_movk_i32 s10, 0x4000
	s_cbranch_execz .LBB0_221
	s_branch .LBB0_286

.LBB0_254:
	v_add_f32_e32 v230, v128, v172
	v_add_f32_e32 v231, v174, v176
	v_add_f32_e32 v230, v177, v230
	v_add_f32_e32 v231, v180, v231
	s_waitcnt lgkmcnt(7)
	v_mfma_f32_32x32x16_bf16 v[82:97], v[66:69], v[98:101], 0
	v_add_f32_e32 v230, v181, v230
	v_add_f32_e32 v231, v183, v231
	v_add_f32_e32 v230, v184, v230
	v_add_f32_e32 v231, v185, v231
	s_waitcnt lgkmcnt(6)
	v_mfma_f32_32x32x16_bf16 v[66:81], v[70:73], v[98:101], 0
	v_add_f32_e32 v230, v186, v230
	v_add_f32_e32 v231, v188, v231
	v_add_f32_e32 v230, v187, v230
	v_add_f32_e32 v231, v189, v231
	s_add_i32 s10, s28, 2
	s_max_i32 s96, s10, 0
	s_lshl_b64 s[12:13], s[96:97], 19
	s_add_u32 s10, s74, s12
	s_addc_u32 s11, s75, s13
	s_mov_b32 s14, m0
	s_mov_b32 m0, s51
	s_nop 0
	global_load_lds_dwordx4 v156, s[10:11]
	s_mov_b32 m0, s14
	s_add_u32 s8, s89, s8
	s_addc_u32 s9, s90, s9
	s_mov_b32 s10, m0
	s_mov_b32 m0, s46
	s_nop 0
	global_load_lds_dwordx4 v154, s[8:9]
	s_mov_b32 m0, s10
	s_nop 0
	s_mov_b32 s10, m0
	s_mov_b32 m0, s76
	s_nop 0
	global_load_lds_dwordx4 v155, s[8:9]
	s_mov_b32 m0, s10
	s_waitcnt lgkmcnt(5)
	v_mfma_f32_32x32x16_bf16 v[82:97], v[210:213], v[102:105], v[82:97]
	v_add_f32_e32 v230, v190, v230
	v_add_f32_e32 v231, v191, v231
	v_add_f32_e32 v230, v121, v230
	v_add_f32_e32 v231, v122, v231
	s_waitcnt lgkmcnt(4)
	v_mfma_f32_32x32x16_bf16 v[66:81], v[214:217], v[102:105], v[66:81]
	v_add_f32_e32 v230, v123, v230
	v_add_f32_e32 v231, v124, v231
	v_add_f32_e32 v230, v125, v230
	v_add_f32_e32 v231, v126, v231
	s_waitcnt lgkmcnt(3)
	v_mfma_f32_32x32x16_bf16 v[82:97], v[218:221], v[106:109], v[82:97]
	v_add_f32_e32 v230, v127, v230
	v_add_f32_e32 v231, v129, v231
	v_add_f32_e32 v230, v142, v230
	v_add_f32_e32 v231, v175, v231
	s_waitcnt lgkmcnt(2)
	v_mfma_f32_32x32x16_bf16 v[66:81], v[222:225], v[106:109], v[66:81]
	v_add_f32_e32 v230, v173, v230
	v_add_f32_e32 v231, v178, v231
	v_add_f32_e32 v230, v179, v230
	v_add_f32_e32 v231, v182, v231
	s_waitcnt lgkmcnt(1)
	v_mfma_f32_32x32x16_bf16 v[82:97], v[226:229], v[110:113], v[82:97]
	v_add_f32_e32 v230, v192, v230
	v_add_f32_e32 v231, v193, v231
	v_add_f32_e32 v230, v230, v231
	v_add_f32_e32 v118, v118, v230
	s_waitcnt lgkmcnt(0)
	v_mfma_f32_32x32x16_bf16 v[66:81], v[234:237], v[110:113], v[66:81]
	s_add_i32 s8, s79, 1
	v_cvt_f32_i32_e32 v238, s8
	v_or_b32_sdwa v132, v238, v157 dst_sel:DWORD dst_unused:UNUSED_PAD src0_sel:WORD_1 src1_sel:DWORD
	v_or_b32_sdwa v133, v238, v157 dst_sel:DWORD dst_unused:UNUSED_PAD src0_sel:WORD_1 src1_sel:DWORD
	ds_read_b64_tr_b16 v[210:211], v146 offset:16384
	ds_read_b64_tr_b16 v[212:213], v147 offset:16384
	ds_read_b64_tr_b16 v[214:215], v148 offset:16384
	ds_read_b64_tr_b16 v[216:217], v149 offset:16384
	v_mfma_f32_32x32x16_bf16 v[82:97], v[132:135], v[114:117], v[82:97]
	v_or_b32_sdwa v132, v238, v158 dst_sel:DWORD dst_unused:UNUSED_PAD src0_sel:WORD_1 src1_sel:DWORD
	v_or_b32_sdwa v133, v238, v158 dst_sel:DWORD dst_unused:UNUSED_PAD src0_sel:WORD_1 src1_sel:DWORD
	ds_read_b64_tr_b16 v[218:219], v150 offset:16384
	ds_read_b64_tr_b16 v[220:221], v151 offset:16384
	ds_read_b64_tr_b16 v[222:223], v152 offset:16384
	ds_read_b64_tr_b16 v[224:225], v153 offset:16384
	v_mfma_f32_32x32x16_bf16 v[66:81], v[132:135], v[114:117], v[66:81]
	ds_read_b64_tr_b16 v[226:227], v146 offset:20480
	ds_read_b64_tr_b16 v[228:229], v147 offset:20480
	ds_read_b64_tr_b16 v[234:235], v148 offset:20480
	ds_read_b64_tr_b16 v[236:237], v149 offset:20480
	v_cvt_pk_bf16_f32 v194, v128, v174
	v_cvt_pk_bf16_f32 v195, v172, v176
	v_cvt_pk_bf16_f32 v196, v177, v180
	v_cvt_pk_bf16_f32 v197, v181, v183
	v_cvt_pk_bf16_f32 v198, v184, v185
	v_cvt_pk_bf16_f32 v199, v186, v188
	v_cvt_pk_bf16_f32 v200, v187, v189
	v_cvt_pk_bf16_f32 v201, v190, v191
	v_cvt_pk_bf16_f32 v202, v121, v122
	v_cvt_pk_bf16_f32 v203, v123, v124
	v_cvt_pk_bf16_f32 v204, v125, v126
	v_cvt_pk_bf16_f32 v205, v127, v129
	v_cvt_pk_bf16_f32 v206, v142, v175
	v_cvt_pk_bf16_f32 v207, v173, v178
	v_cvt_pk_bf16_f32 v208, v179, v182
	v_cvt_pk_bf16_f32 v209, v192, v193
	s_cmp_lg_u32 s73, -5
	s_cselect_b64 s[8:9], -1, 0
	s_cmp_eq_u32 s73, -5
	s_cselect_b64 s[14:15], -1, 0
	s_and_b64 vcc, exec, s[8:9]
	s_cbranch_vccnz .LBB0_256
	v_sub_f32_e32 v230, 0, v159
	v_sub_f32_e32 v231, 0x3f800000, v159
	v_max_f32_e32 v230, 0, v230
	v_max_f32_e32 v231, 0, v231
	v_pk_fma_f32 v[82:83], s[16:17], v[230:231], v[82:83] neg_lo:[1,0,0] neg_hi:[1,0,0]
	v_sub_f32_e32 v238, 0x40000000, v159
	v_sub_f32_e32 v239, 0x40400000, v159
	v_max_f32_e32 v238, 0, v238
	v_max_f32_e32 v239, 0, v239
	v_pk_fma_f32 v[84:85], s[16:17], v[238:239], v[84:85] neg_lo:[1,0,0] neg_hi:[1,0,0]
	v_sub_f32_e32 v230, 0x40800000, v159
	v_sub_f32_e32 v231, 0x40a00000, v159
	v_max_f32_e32 v230, 0, v230
	v_max_f32_e32 v231, 0, v231
	v_pk_fma_f32 v[86:87], s[16:17], v[230:231], v[86:87] neg_lo:[1,0,0] neg_hi:[1,0,0]
	v_sub_f32_e32 v238, 0x40c00000, v159
	v_sub_f32_e32 v239, 0x40e00000, v159
	v_max_f32_e32 v238, 0, v238
	v_max_f32_e32 v239, 0, v239
	v_pk_fma_f32 v[88:89], s[16:17], v[238:239], v[88:89] neg_lo:[1,0,0] neg_hi:[1,0,0]
	v_sub_f32_e32 v230, 0x41800000, v159
	v_sub_f32_e32 v231, 0x41880000, v159
	v_max_f32_e32 v230, 0, v230
	v_max_f32_e32 v231, 0, v231
	v_pk_fma_f32 v[90:91], s[16:17], v[230:231], v[90:91] neg_lo:[1,0,0] neg_hi:[1,0,0]
	v_sub_f32_e32 v238, 0x41900000, v159
	v_sub_f32_e32 v239, 0x41980000, v159
	v_max_f32_e32 v238, 0, v238
	v_max_f32_e32 v239, 0, v239
	v_pk_fma_f32 v[92:93], s[16:17], v[238:239], v[92:93] neg_lo:[1,0,0] neg_hi:[1,0,0]
	v_sub_f32_e32 v230, 0x41a00000, v159
	v_sub_f32_e32 v231, 0x41a80000, v159
	v_max_f32_e32 v230, 0, v230
	v_max_f32_e32 v231, 0, v231
	v_pk_fma_f32 v[94:95], s[16:17], v[230:231], v[94:95] neg_lo:[1,0,0] neg_hi:[1,0,0]
	v_sub_f32_e32 v238, 0x41b00000, v159
	v_sub_f32_e32 v239, 0x41b80000, v159
	v_max_f32_e32 v238, 0, v238
	v_max_f32_e32 v239, 0, v239
	v_pk_fma_f32 v[96:97], s[16:17], v[238:239], v[96:97] neg_lo:[1,0,0] neg_hi:[1,0,0]
	v_sub_f32_e32 v230, 0x42000000, v159
	v_sub_f32_e32 v231, 0x42040000, v159
	v_max_f32_e32 v230, 0, v230
	v_max_f32_e32 v231, 0, v231
	v_pk_fma_f32 v[66:67], s[16:17], v[230:231], v[66:67] neg_lo:[1,0,0] neg_hi:[1,0,0]
	v_sub_f32_e32 v238, 0x42080000, v159
	v_sub_f32_e32 v239, 0x420c0000, v159
	v_max_f32_e32 v238, 0, v238
	v_max_f32_e32 v239, 0, v239
	v_pk_fma_f32 v[68:69], s[16:17], v[238:239], v[68:69] neg_lo:[1,0,0] neg_hi:[1,0,0]
	v_sub_f32_e32 v230, 0x42100000, v159
	v_sub_f32_e32 v231, 0x42140000, v159
	v_max_f32_e32 v230, 0, v230
	v_max_f32_e32 v231, 0, v231
	v_pk_fma_f32 v[70:71], s[16:17], v[230:231], v[70:71] neg_lo:[1,0,0] neg_hi:[1,0,0]
	v_sub_f32_e32 v238, 0x42180000, v159
	v_sub_f32_e32 v239, 0x421c0000, v159
	v_max_f32_e32 v238, 0, v238
	v_max_f32_e32 v239, 0, v239
	v_pk_fma_f32 v[72:73], s[16:17], v[238:239], v[72:73] neg_lo:[1,0,0] neg_hi:[1,0,0]
	v_sub_f32_e32 v230, 0x42400000, v159
	v_sub_f32_e32 v231, 0x42440000, v159
	v_max_f32_e32 v230, 0, v230
	v_max_f32_e32 v231, 0, v231
	v_pk_fma_f32 v[74:75], s[16:17], v[230:231], v[74:75] neg_lo:[1,0,0] neg_hi:[1,0,0]
	v_sub_f32_e32 v238, 0x42480000, v159
	v_sub_f32_e32 v239, 0x424c0000, v159
	v_max_f32_e32 v238, 0, v238
	v_max_f32_e32 v239, 0, v239
	v_pk_fma_f32 v[76:77], s[16:17], v[238:239], v[76:77] neg_lo:[1,0,0] neg_hi:[1,0,0]
	v_sub_f32_e32 v230, 0x42500000, v159
	v_sub_f32_e32 v231, 0x42540000, v159
	v_max_f32_e32 v230, 0, v230
	v_max_f32_e32 v231, 0, v231
	v_pk_fma_f32 v[78:79], s[16:17], v[230:231], v[78:79] neg_lo:[1,0,0] neg_hi:[1,0,0]
	v_sub_f32_e32 v238, 0x42580000, v159
	v_sub_f32_e32 v239, 0x425c0000, v159
	v_max_f32_e32 v238, 0, v238
	v_max_f32_e32 v239, 0, v239
	v_pk_fma_f32 v[80:81], s[16:17], v[238:239], v[80:81] neg_lo:[1,0,0] neg_hi:[1,0,0]

.LBB0_262:
	s_waitcnt lgkmcnt(10)
	v_mfma_f32_32x32x16_bf16 v[2:17], v[210:213], v[194:197], v[2:17]
	ds_read_b64_tr_b16 v[210:211], v150 offset:20480
	ds_read_b64_tr_b16 v[212:213], v151 offset:20480
	v_exp_f32_e32 v121, v66
	v_exp_f32_e32 v122, v67
	s_waitcnt lgkmcnt(10)
	v_mfma_f32_32x32x16_bf16 v[18:33], v[214:217], v[194:197], v[18:33]
	ds_read_b64_tr_b16 v[214:215], v152 offset:20480
	ds_read_b64_tr_b16 v[216:217], v153 offset:20480
	v_exp_f32_e32 v123, v68
	v_exp_f32_e32 v124, v69
	s_waitcnt lgkmcnt(10)
	v_mfma_f32_32x32x16_bf16 v[34:49], v[218:221], v[194:197], v[34:49]
	ds_read_b64_tr_b16 v[218:219], v146 offset:24576
	ds_read_b64_tr_b16 v[220:221], v147 offset:24576
	v_exp_f32_e32 v125, v70
	v_exp_f32_e32 v126, v71
	s_waitcnt lgkmcnt(10)
	v_mfma_f32_32x32x16_bf16 v[50:65], v[222:225], v[194:197], v[50:65]
	ds_read_b64_tr_b16 v[222:223], v148 offset:24576
	ds_read_b64_tr_b16 v[224:225], v149 offset:24576
	v_exp_f32_e32 v127, v72
	v_exp_f32_e32 v129, v73
	v_mov_b32_e32 v238, 0x18020
	ds_read_b128 v[66:69], v238
	v_mov_b32_e32 v239, 0x18030
	ds_read_b128 v[70:73], v239
	s_waitcnt lgkmcnt(12)
	v_mfma_f32_32x32x16_bf16 v[2:17], v[226:229], v[198:201], v[2:17]
	ds_read_b64_tr_b16 v[226:227], v150 offset:24576
	ds_read_b64_tr_b16 v[228:229], v151 offset:24576
	v_exp_f32_e32 v128, v82
	v_exp_f32_e32 v174, v83
	s_waitcnt lgkmcnt(12)
	v_mfma_f32_32x32x16_bf16 v[18:33], v[234:237], v[198:201], v[18:33]
	ds_read_b64_tr_b16 v[234:235], v152 offset:24576
	ds_read_b64_tr_b16 v[236:237], v153 offset:24576
	v_exp_f32_e32 v172, v84
	v_exp_f32_e32 v176, v85
	s_waitcnt lgkmcnt(12)
	v_mfma_f32_32x32x16_bf16 v[34:49], v[210:213], v[198:201], v[34:49]
	ds_read_b64_tr_b16 v[210:211], v146 offset:28672
	ds_read_b64_tr_b16 v[212:213], v147 offset:28672
	v_exp_f32_e32 v177, v86
	v_exp_f32_e32 v180, v87
	s_waitcnt lgkmcnt(12)
	v_mfma_f32_32x32x16_bf16 v[50:65], v[214:217], v[198:201], v[50:65]
	ds_read_b64_tr_b16 v[214:215], v148 offset:28672
	ds_read_b64_tr_b16 v[216:217], v149 offset:28672
	v_exp_f32_e32 v181, v88
	v_exp_f32_e32 v183, v89
	s_waitcnt lgkmcnt(12)
	v_mfma_f32_32x32x16_bf16 v[2:17], v[218:221], v[202:205], v[2:17]
	ds_read_b64_tr_b16 v[218:219], v150 offset:28672
	ds_read_b64_tr_b16 v[220:221], v151 offset:28672
	v_exp_f32_e32 v184, v90
	v_exp_f32_e32 v185, v91
	s_waitcnt lgkmcnt(12)
	v_mfma_f32_32x32x16_bf16 v[18:33], v[222:225], v[202:205], v[18:33]
	ds_read_b64_tr_b16 v[222:223], v152 offset:28672
	ds_read_b64_tr_b16 v[224:225], v153 offset:28672
	v_exp_f32_e32 v186, v92
	v_exp_f32_e32 v188, v93
	s_waitcnt lgkmcnt(10)
	v_mfma_f32_32x32x16_bf16 v[34:49], v[226:229], v[202:205], v[34:49]
	v_exp_f32_e32 v187, v94
	v_exp_f32_e32 v189, v95
	s_waitcnt lgkmcnt(8)
	v_mfma_f32_32x32x16_bf16 v[50:65], v[234:237], v[202:205], v[50:65]
	v_exp_f32_e32 v190, v96
	v_exp_f32_e32 v191, v97
	s_waitcnt lgkmcnt(6)
	v_mfma_f32_32x32x16_bf16 v[2:17], v[210:213], v[206:209], v[2:17]
	v_exp_f32_e32 v142, v74
	v_exp_f32_e32 v175, v75
	v_and_b32_e32 v66, v66, v67
	v_and_b32_e32 v68, v68, v69
	s_waitcnt lgkmcnt(4)
	v_mfma_f32_32x32x16_bf16 v[18:33], v[214:217], v[206:209], v[18:33]
	v_exp_f32_e32 v173, v76
	v_exp_f32_e32 v178, v77
	v_and_b32_e32 v70, v70, v71
	v_and_b32_e32 v72, v72, v73
	s_waitcnt lgkmcnt(2)
	v_mfma_f32_32x32x16_bf16 v[34:49], v[218:221], v[206:209], v[34:49]
	v_exp_f32_e32 v179, v78
	v_exp_f32_e32 v182, v79
	v_and_b32_e32 v66, v66, v68
	v_and_b32_e32 v70, v70, v72
	s_waitcnt lgkmcnt(0)
	v_mfma_f32_32x32x16_bf16 v[50:65], v[222:225], v[206:209], v[50:65]
	v_exp_f32_e32 v192, v80
	v_exp_f32_e32 v193, v81
	v_and_b32_e32 v66, v66, v70
	s_andn2_b64 vcc, exec, s[14:15]
	s_cbranch_vccz .LBB0_269
	s_cmp_gt_i32 s3, s82
	v_mov_b32_e32 v238, 0
	s_cbranch_scc0 .LBB0_270

.LBB0_266:
	s_or_b64 exec, exec, s[8:9]
	s_waitcnt vmcnt(6) lgkmcnt(0)
	s_barrier
	v_cmp_ne_u32_e32 vcc, 0, v66
	ds_read_b128 v[66:69], v168 offset:24576
	ds_read_b128 v[70:73], v168 offset:28672
	ds_read_b128 v[210:213], v169 offset:24576
	ds_read_b128 v[214:217], v169 offset:28672
	ds_read_b128 v[218:221], v170 offset:24576
	ds_read_b128 v[222:225], v170 offset:28672
	ds_read_b128 v[226:229], v171 offset:24576
	ds_read_b128 v[234:237], v171 offset:28672
	s_cbranch_vccz .LBB0_271
	s_mov_b64 s[8:9], -1
	s_mov_b32 s10, 0x8000

.LBB0_271:
	v_add_f32_e32 v230, v128, v172
	v_add_f32_e32 v231, v174, v176
	v_add_f32_e32 v230, v177, v230
	v_add_f32_e32 v231, v180, v231
	s_waitcnt lgkmcnt(7)
	v_mfma_f32_32x32x16_bf16 v[82:97], v[66:69], v[98:101], 0
	v_add_f32_e32 v230, v181, v230
	v_add_f32_e32 v231, v183, v231
	v_add_f32_e32 v230, v184, v230
	v_add_f32_e32 v231, v185, v231
	s_waitcnt lgkmcnt(6)
	v_mfma_f32_32x32x16_bf16 v[66:81], v[70:73], v[98:101], 0
	v_add_f32_e32 v230, v186, v230
	v_add_f32_e32 v231, v188, v231
	v_add_f32_e32 v230, v187, v230
	v_add_f32_e32 v231, v189, v231
	s_add_i32 s2, s28, 1
	s_max_i32 s96, s2, 0
	s_lshl_b64 s[2:3], s[96:97], 19
	s_add_u32 s2, s74, s2
	s_addc_u32 s3, s75, s3
	s_mov_b32 s8, m0
	s_mov_b32 m0, s53
	s_nop 0
	global_load_lds_dwordx4 v156, s[2:3]
	s_mov_b32 m0, s8
	s_add_u32 s2, s89, s12
	s_addc_u32 s3, s90, s13
	s_mov_b32 s8, m0
	s_mov_b32 m0, s52
	s_nop 0
	global_load_lds_dwordx4 v154, s[2:3]
	s_mov_b32 m0, s8
	s_nop 0
	s_mov_b32 s8, m0
	s_mov_b32 m0, s77
	s_nop 0
	global_load_lds_dwordx4 v155, s[2:3]
	s_mov_b32 m0, s8
	s_waitcnt lgkmcnt(5)
	v_mfma_f32_32x32x16_bf16 v[82:97], v[210:213], v[102:105], v[82:97]
	v_add_f32_e32 v230, v190, v230
	v_add_f32_e32 v231, v191, v231
	v_add_f32_e32 v230, v121, v230
	v_add_f32_e32 v231, v122, v231
	s_waitcnt lgkmcnt(4)
	v_mfma_f32_32x32x16_bf16 v[66:81], v[214:217], v[102:105], v[66:81]
	v_add_f32_e32 v230, v123, v230
	v_add_f32_e32 v231, v124, v231
	v_add_f32_e32 v230, v125, v230
	v_add_f32_e32 v231, v126, v231
	s_waitcnt lgkmcnt(3)
	v_mfma_f32_32x32x16_bf16 v[82:97], v[218:221], v[106:109], v[82:97]
	v_add_f32_e32 v230, v127, v230
	v_add_f32_e32 v231, v129, v231
	v_add_f32_e32 v230, v142, v230
	v_add_f32_e32 v231, v175, v231
	s_waitcnt lgkmcnt(2)
	v_mfma_f32_32x32x16_bf16 v[66:81], v[222:225], v[106:109], v[66:81]
	v_add_f32_e32 v230, v173, v230
	v_add_f32_e32 v231, v178, v231
	v_add_f32_e32 v230, v179, v230
	v_add_f32_e32 v231, v182, v231
	s_waitcnt lgkmcnt(1)
	v_mfma_f32_32x32x16_bf16 v[82:97], v[226:229], v[110:113], v[82:97]
	v_add_f32_e32 v230, v192, v230
	v_add_f32_e32 v231, v193, v231
	v_add_f32_e32 v230, v230, v231
	v_add_f32_e32 v118, v118, v230
	s_waitcnt lgkmcnt(0)
	v_mfma_f32_32x32x16_bf16 v[66:81], v[234:237], v[110:113], v[66:81]
	v_cvt_f32_i32_e32 v238, s79
	v_or_b32_sdwa v132, v238, v157 dst_sel:DWORD dst_unused:UNUSED_PAD src0_sel:WORD_1 src1_sel:DWORD
	v_or_b32_sdwa v133, v238, v157 dst_sel:DWORD dst_unused:UNUSED_PAD src0_sel:WORD_1 src1_sel:DWORD
	ds_read_b64_tr_b16 v[210:211], v146 offset:32768
	ds_read_b64_tr_b16 v[212:213], v147 offset:32768
	ds_read_b64_tr_b16 v[214:215], v148 offset:32768
	ds_read_b64_tr_b16 v[216:217], v149 offset:32768
	v_mfma_f32_32x32x16_bf16 v[82:97], v[132:135], v[114:117], v[82:97]
	v_or_b32_sdwa v132, v238, v158 dst_sel:DWORD dst_unused:UNUSED_PAD src0_sel:WORD_1 src1_sel:DWORD
	v_or_b32_sdwa v133, v238, v158 dst_sel:DWORD dst_unused:UNUSED_PAD src0_sel:WORD_1 src1_sel:DWORD
	ds_read_b64_tr_b16 v[218:219], v150 offset:32768
	ds_read_b64_tr_b16 v[220:221], v151 offset:32768
	ds_read_b64_tr_b16 v[222:223], v152 offset:32768
	ds_read_b64_tr_b16 v[224:225], v153 offset:32768
	v_mfma_f32_32x32x16_bf16 v[66:81], v[132:135], v[114:117], v[66:81]
	ds_read_b64_tr_b16 v[226:227], v146 offset:36864
	ds_read_b64_tr_b16 v[228:229], v147 offset:36864
	ds_read_b64_tr_b16 v[234:235], v148 offset:36864
	ds_read_b64_tr_b16 v[236:237], v149 offset:36864
	v_cvt_pk_bf16_f32 v194, v128, v174
	v_cvt_pk_bf16_f32 v195, v172, v176
	v_cvt_pk_bf16_f32 v196, v177, v180
	v_cvt_pk_bf16_f32 v197, v181, v183
	v_cvt_pk_bf16_f32 v198, v184, v185
	v_cvt_pk_bf16_f32 v199, v186, v188
	v_cvt_pk_bf16_f32 v200, v187, v189
	v_cvt_pk_bf16_f32 v201, v190, v191
	v_cvt_pk_bf16_f32 v202, v121, v122
	v_cvt_pk_bf16_f32 v203, v123, v124
	v_cvt_pk_bf16_f32 v204, v125, v126
	v_cvt_pk_bf16_f32 v205, v127, v129
	v_cvt_pk_bf16_f32 v206, v142, v175
	v_cvt_pk_bf16_f32 v207, v173, v178
	v_cvt_pk_bf16_f32 v208, v179, v182
	v_cvt_pk_bf16_f32 v209, v192, v193
	s_cmp_lg_u32 s73, -4
	s_cselect_b64 s[8:9], -1, 0
	s_cmp_eq_u32 s73, -4
	s_cselect_b64 s[12:13], -1, 0
	s_and_b64 vcc, exec, s[8:9]
	s_cbranch_vccnz .LBB0_273
	v_sub_f32_e32 v230, 0, v159
	v_sub_f32_e32 v231, 0x3f800000, v159
	v_max_f32_e32 v230, 0, v230
	v_max_f32_e32 v231, 0, v231
	v_pk_fma_f32 v[82:83], s[16:17], v[230:231], v[82:83] neg_lo:[1,0,0] neg_hi:[1,0,0]
	v_sub_f32_e32 v238, 0x40000000, v159
	v_sub_f32_e32 v239, 0x40400000, v159
	v_max_f32_e32 v238, 0, v238
	v_max_f32_e32 v239, 0, v239
	v_pk_fma_f32 v[84:85], s[16:17], v[238:239], v[84:85] neg_lo:[1,0,0] neg_hi:[1,0,0]
	v_sub_f32_e32 v230, 0x40800000, v159
	v_sub_f32_e32 v231, 0x40a00000, v159
	v_max_f32_e32 v230, 0, v230
	v_max_f32_e32 v231, 0, v231
	v_pk_fma_f32 v[86:87], s[16:17], v[230:231], v[86:87] neg_lo:[1,0,0] neg_hi:[1,0,0]
	v_sub_f32_e32 v238, 0x40c00000, v159
	v_sub_f32_e32 v239, 0x40e00000, v159
	v_max_f32_e32 v238, 0, v238
	v_max_f32_e32 v239, 0, v239
	v_pk_fma_f32 v[88:89], s[16:17], v[238:239], v[88:89] neg_lo:[1,0,0] neg_hi:[1,0,0]
	v_sub_f32_e32 v230, 0x41800000, v159
	v_sub_f32_e32 v231, 0x41880000, v159
	v_max_f32_e32 v230, 0, v230
	v_max_f32_e32 v231, 0, v231
	v_pk_fma_f32 v[90:91], s[16:17], v[230:231], v[90:91] neg_lo:[1,0,0] neg_hi:[1,0,0]
	v_sub_f32_e32 v238, 0x41900000, v159
	v_sub_f32_e32 v239, 0x41980000, v159
	v_max_f32_e32 v238, 0, v238
	v_max_f32_e32 v239, 0, v239
	v_pk_fma_f32 v[92:93], s[16:17], v[238:239], v[92:93] neg_lo:[1,0,0] neg_hi:[1,0,0]
	v_sub_f32_e32 v230, 0x41a00000, v159
	v_sub_f32_e32 v231, 0x41a80000, v159
	v_max_f32_e32 v230, 0, v230
	v_max_f32_e32 v231, 0, v231
	v_pk_fma_f32 v[94:95], s[16:17], v[230:231], v[94:95] neg_lo:[1,0,0] neg_hi:[1,0,0]
	v_sub_f32_e32 v238, 0x41b00000, v159
	v_sub_f32_e32 v239, 0x41b80000, v159
	v_max_f32_e32 v238, 0, v238
	v_max_f32_e32 v239, 0, v239
	v_pk_fma_f32 v[96:97], s[16:17], v[238:239], v[96:97] neg_lo:[1,0,0] neg_hi:[1,0,0]
	v_sub_f32_e32 v230, 0x42000000, v159
	v_sub_f32_e32 v231, 0x42040000, v159
	v_max_f32_e32 v230, 0, v230
	v_max_f32_e32 v231, 0, v231
	v_pk_fma_f32 v[66:67], s[16:17], v[230:231], v[66:67] neg_lo:[1,0,0] neg_hi:[1,0,0]
	v_sub_f32_e32 v238, 0x42080000, v159
	v_sub_f32_e32 v239, 0x420c0000, v159
	v_max_f32_e32 v238, 0, v238
	v_max_f32_e32 v239, 0, v239
	v_pk_fma_f32 v[68:69], s[16:17], v[238:239], v[68:69] neg_lo:[1,0,0] neg_hi:[1,0,0]
	v_sub_f32_e32 v230, 0x42100000, v159
	v_sub_f32_e32 v231, 0x42140000, v159
	v_max_f32_e32 v230, 0, v230
	v_max_f32_e32 v231, 0, v231
	v_pk_fma_f32 v[70:71], s[16:17], v[230:231], v[70:71] neg_lo:[1,0,0] neg_hi:[1,0,0]
	v_sub_f32_e32 v238, 0x42180000, v159
	v_sub_f32_e32 v239, 0x421c0000, v159
	v_max_f32_e32 v238, 0, v238
	v_max_f32_e32 v239, 0, v239
	v_pk_fma_f32 v[72:73], s[16:17], v[238:239], v[72:73] neg_lo:[1,0,0] neg_hi:[1,0,0]
	v_sub_f32_e32 v230, 0x42400000, v159
	v_sub_f32_e32 v231, 0x42440000, v159
	v_max_f32_e32 v230, 0, v230
	v_max_f32_e32 v231, 0, v231
	v_pk_fma_f32 v[74:75], s[16:17], v[230:231], v[74:75] neg_lo:[1,0,0] neg_hi:[1,0,0]
	v_sub_f32_e32 v238, 0x42480000, v159
	v_sub_f32_e32 v239, 0x424c0000, v159
	v_max_f32_e32 v238, 0, v238
	v_max_f32_e32 v239, 0, v239
	v_pk_fma_f32 v[76:77], s[16:17], v[238:239], v[76:77] neg_lo:[1,0,0] neg_hi:[1,0,0]
	v_sub_f32_e32 v230, 0x42500000, v159
	v_sub_f32_e32 v231, 0x42540000, v159
	v_max_f32_e32 v230, 0, v230
	v_max_f32_e32 v231, 0, v231
	v_pk_fma_f32 v[78:79], s[16:17], v[230:231], v[78:79] neg_lo:[1,0,0] neg_hi:[1,0,0]
	v_sub_f32_e32 v238, 0x42580000, v159
	v_sub_f32_e32 v239, 0x425c0000, v159
	v_max_f32_e32 v238, 0, v238
	v_max_f32_e32 v239, 0, v239
	v_pk_fma_f32 v[80:81], s[16:17], v[238:239], v[80:81] neg_lo:[1,0,0] neg_hi:[1,0,0]

.LBB0_279:
	s_waitcnt lgkmcnt(10)
	v_mfma_f32_32x32x16_bf16 v[2:17], v[210:213], v[194:197], v[2:17]
	ds_read_b64_tr_b16 v[210:211], v150 offset:36864
	ds_read_b64_tr_b16 v[212:213], v151 offset:36864
	v_exp_f32_e32 v121, v66
	v_exp_f32_e32 v122, v67
	s_waitcnt lgkmcnt(10)
	v_mfma_f32_32x32x16_bf16 v[18:33], v[214:217], v[194:197], v[18:33]
	ds_read_b64_tr_b16 v[214:215], v152 offset:36864
	ds_read_b64_tr_b16 v[216:217], v153 offset:36864
	v_exp_f32_e32 v123, v68
	v_exp_f32_e32 v124, v69
	s_waitcnt lgkmcnt(10)
	v_mfma_f32_32x32x16_bf16 v[34:49], v[218:221], v[194:197], v[34:49]
	ds_read_b64_tr_b16 v[218:219], v146 offset:40960
	ds_read_b64_tr_b16 v[220:221], v147 offset:40960
	v_exp_f32_e32 v125, v70
	v_exp_f32_e32 v126, v71
	s_waitcnt lgkmcnt(10)
	v_mfma_f32_32x32x16_bf16 v[50:65], v[222:225], v[194:197], v[50:65]
	ds_read_b64_tr_b16 v[222:223], v148 offset:40960
	ds_read_b64_tr_b16 v[224:225], v149 offset:40960
	v_exp_f32_e32 v127, v72
	v_exp_f32_e32 v129, v73
	v_mov_b32_e32 v238, 0x18000
	ds_read_b128 v[66:69], v238
	v_mov_b32_e32 v239, 0x18010
	ds_read_b128 v[70:73], v239
	s_waitcnt lgkmcnt(12)
	v_mfma_f32_32x32x16_bf16 v[2:17], v[226:229], v[198:201], v[2:17]
	ds_read_b64_tr_b16 v[226:227], v150 offset:40960
	ds_read_b64_tr_b16 v[228:229], v151 offset:40960
	v_exp_f32_e32 v128, v82
	v_exp_f32_e32 v174, v83
	s_waitcnt lgkmcnt(12)
	v_mfma_f32_32x32x16_bf16 v[18:33], v[234:237], v[198:201], v[18:33]
	ds_read_b64_tr_b16 v[234:235], v152 offset:40960
	ds_read_b64_tr_b16 v[236:237], v153 offset:40960
	v_exp_f32_e32 v172, v84
	v_exp_f32_e32 v176, v85
	s_waitcnt lgkmcnt(12)
	v_mfma_f32_32x32x16_bf16 v[34:49], v[210:213], v[198:201], v[34:49]
	ds_read_b64_tr_b16 v[210:211], v146 offset:45056
	ds_read_b64_tr_b16 v[212:213], v147 offset:45056
	v_exp_f32_e32 v177, v86
	v_exp_f32_e32 v180, v87
	s_waitcnt lgkmcnt(12)
	v_mfma_f32_32x32x16_bf16 v[50:65], v[214:217], v[198:201], v[50:65]
	ds_read_b64_tr_b16 v[214:215], v148 offset:45056
	ds_read_b64_tr_b16 v[216:217], v149 offset:45056
	v_exp_f32_e32 v181, v88
	v_exp_f32_e32 v183, v89
	s_waitcnt lgkmcnt(12)
	v_mfma_f32_32x32x16_bf16 v[2:17], v[218:221], v[202:205], v[2:17]
	ds_read_b64_tr_b16 v[218:219], v150 offset:45056
	ds_read_b64_tr_b16 v[220:221], v151 offset:45056
	v_exp_f32_e32 v184, v90
	v_exp_f32_e32 v185, v91
	s_waitcnt lgkmcnt(12)
	v_mfma_f32_32x32x16_bf16 v[18:33], v[222:225], v[202:205], v[18:33]
	ds_read_b64_tr_b16 v[222:223], v152 offset:45056
	ds_read_b64_tr_b16 v[224:225], v153 offset:45056
	v_exp_f32_e32 v186, v92
	v_exp_f32_e32 v188, v93
	s_waitcnt lgkmcnt(10)
	v_mfma_f32_32x32x16_bf16 v[34:49], v[226:229], v[202:205], v[34:49]
	v_exp_f32_e32 v187, v94
	v_exp_f32_e32 v189, v95
	s_waitcnt lgkmcnt(8)
	v_mfma_f32_32x32x16_bf16 v[50:65], v[234:237], v[202:205], v[50:65]
	v_exp_f32_e32 v190, v96
	v_exp_f32_e32 v191, v97
	s_waitcnt lgkmcnt(6)
	v_mfma_f32_32x32x16_bf16 v[2:17], v[210:213], v[206:209], v[2:17]
	v_exp_f32_e32 v142, v74
	v_exp_f32_e32 v175, v75
	v_and_b32_e32 v66, v66, v67
	v_and_b32_e32 v68, v68, v69
	s_waitcnt lgkmcnt(4)
	v_mfma_f32_32x32x16_bf16 v[18:33], v[214:217], v[206:209], v[18:33]
	v_exp_f32_e32 v173, v76
	v_exp_f32_e32 v178, v77
	v_and_b32_e32 v70, v70, v71
	v_and_b32_e32 v72, v72, v73
	s_waitcnt lgkmcnt(2)
	v_mfma_f32_32x32x16_bf16 v[34:49], v[218:221], v[206:209], v[34:49]
	v_exp_f32_e32 v179, v78
	v_exp_f32_e32 v182, v79
	v_and_b32_e32 v66, v66, v68
	v_and_b32_e32 v70, v70, v72
	s_waitcnt lgkmcnt(0)
	v_mfma_f32_32x32x16_bf16 v[50:65], v[222:225], v[206:209], v[50:65]
	v_exp_f32_e32 v192, v80
	v_exp_f32_e32 v193, v81
	v_and_b32_e32 v66, v66, v70
	s_andn2_b64 vcc, exec, s[12:13]
	s_cbranch_vccz .LBB0_284
	s_add_i32 s28, s28, 4
	s_cmp_gt_i32 s28, s82
	v_mov_b32_e32 v238, 0
	s_cbranch_scc0 .LBB0_285

; __device__ __forceinline__ void diff_unit(LAS unsigned char* lds, const bf16_t* __restrict__ u, bf16_t* __restrict__ yz, float* __restrict__ oscr, const unsigned* __restrict__ kb, int b, int h, int qb, float lam, float slope2, const float* __restrict__ gsub, float out_scale) {
;     ...
;         for (int t = 0; t < NT; t += 4) {
;             PSTEP(sA0, sA1, sB0, sB1, t, 0);
;             PSTEP(sB0, sB1, sA0, sA1, t + 1, 1);
;             PSTEP(sA0, sA1, sB0, sB1, t + 2, 2);
;             PSTEP(sB0, sB1, sA0, sA1, t + 3, 3);
;         }
.LBB0_283:
	s_or_b64 exec, exec, s[8:9]
	s_waitcnt vmcnt(6) lgkmcnt(0)
	s_barrier
	v_cmp_ne_u32_e64 s[8:9], 0, v66
	ds_read_b128 v[66:69], v168
	ds_read_b128 v[70:73], v168 offset:4096
	ds_read_b128 v[210:213], v169
	ds_read_b128 v[214:217], v169 offset:4096
	ds_read_b128 v[218:221], v170
	ds_read_b128 v[222:225], v170 offset:4096
	ds_read_b128 v[226:229], v171
	ds_read_b128 v[234:237], v171 offset:4096
	s_add_i32 s79, s79, -4
	s_addk_i32 s99, 0xff00
	s_add_i32 s48, s48, 0xffe00000
	s_add_i32 s27, s27, 4
	s_mov_b32 s10, 0xc000
	s_and_b64 vcc, exec, s[8:9]
	s_cbranch_vccz .LBB0_221
	s_branch .LBB0_286

; __device__ __forceinline__ s16x4 vtr(LAS unsigned char* p) { return __builtin_bit_cast(s16x4, __builtin_amdgcn_ds_read_tr16_b64_v4i16((LAS v4i16_t*)p)); }
; #define MFMA32(a, b, c) __builtin_amdgcn_mfma_f32_32x32x16_bf16((a), (b), (c), 0, 0, 0)
; #define WAITV_BAR(N) asm volatile("s_waitcnt vmcnt(" #N ") lgkmcnt(0)\n\ts_barrier" ::: "memory")
; #define GA(P, g, k) do { sa_ += P[4 * (g)]; sb_ += P[4 * (g) + 1]; sa_ += P[4 * (g) + 2]; sb_ += P[4 * (g) + 3]; \
;         pw_[k][2 * ((g) & 1)] = cvt_pk_bf16(P[4 * (g)], P[4 * (g) + 1]); pw_[k][2 * ((g) & 1) + 1] = cvt_pk_bf16(P[4 * (g) + 2], P[4 * (g) + 3]); } while (0)
; __device__ __forceinline__ void diff_unit(LAS unsigned char* lds, const bf16_t* __restrict__ u, bf16_t* __restrict__ yz, float* __restrict__ oscr, const unsigned* __restrict__ kb, int b, int h, int qb, float lam, float slope2, const float* __restrict__ gsub, float out_scale) {
;     ...
;         diff_pass_done:
;         {
;             float sa_ = 0.f, sb_ = 0.f;
;             GA(fin0, 0, 0); GA(fin0, 1, 0); GA(fin0, 2, 1); GA(fin0, 3, 1); GA(fin1, 0, 2); GA(fin1, 1, 2); GA(fin1, 2, 3); GA(fin1, 3, 3);
;             l += sa_ + sb_;
;             const unsigned vso = (unsigned)vs_last * 16384u;
; #pragma unroll
;             for (int ks = 0; ks < 4; ++ks)
; #pragma unroll
;                 for (int c = 0; c < 4; ++c) {
;                     const s16x4 a0_ = vtr(lds + vso + vba[c][0] + ks * 4096), a1_ = vtr(lds + vso + vba[c][1] + ks * 4096);
;                     const bf16x8 v_ = (bf16x8){a0_[0], a0_[1], a0_[2], a0_[3], a1_[0], a1_[1], a1_[2], a1_[3]};
;                     o[c] = MFMA32(v_, __builtin_bit_cast(bf16x8, pw_[ks]), o[c]); }
;         }
;         WAITV_BAR(0);
;     ...
;         const float ltot = l + __shfl_xor(l, 32), inv = 1.0f / ltot;
.LBB0_286:
	s_waitcnt lgkmcnt(0)
	s_add_i32 s2, s10, 0
	v_add_u32_e32 v0, s2, v146
	v_add_u32_e32 v86, s2, v147
	ds_read_b64_tr_b16 v[82:83], v0
	ds_read_b64_tr_b16 v[84:85], v86
	v_cvt_pk_bf16_f32 v74, v128, v174
	v_cvt_pk_bf16_f32 v75, v172, v176
	v_cvt_pk_bf16_f32 v76, v177, v180
	v_cvt_pk_bf16_f32 v77, v181, v183
	v_add_u32_e32 v87, s2, v148
	v_add_u32_e32 v88, s2, v149
	s_waitcnt lgkmcnt(0)
	v_mfma_f32_32x32x16_bf16 v[2:17], v[82:85], v[74:77], v[2:17]
	ds_read_b64_tr_b16 v[82:83], v87
	ds_read_b64_tr_b16 v[84:85], v88
	v_add_u32_e32 v89, s2, v150
	v_add_u32_e32 v90, s2, v151
	v_add_u32_e32 v91, s2, v152
	v_add_u32_e32 v92, s2, v153
	v_cvt_pk_bf16_f32 v78, v184, v185
	s_waitcnt lgkmcnt(0)
	v_mfma_f32_32x32x16_bf16 v[18:33], v[82:85], v[74:77], v[18:33]
	ds_read_b64_tr_b16 v[82:83], v89
	ds_read_b64_tr_b16 v[84:85], v90
	v_cvt_pk_bf16_f32 v79, v186, v188
	v_cvt_pk_bf16_f32 v80, v187, v189
	v_cvt_pk_bf16_f32 v81, v190, v191
	v_cvt_pk_bf16_f32 v70, v121, v122
	v_cvt_pk_bf16_f32 v71, v123, v124
	s_waitcnt lgkmcnt(0)
	v_mfma_f32_32x32x16_bf16 v[34:49], v[82:85], v[74:77], v[34:49]
	ds_read_b64_tr_b16 v[82:83], v91
	ds_read_b64_tr_b16 v[84:85], v92
	v_cvt_pk_bf16_f32 v72, v125, v126
	v_cvt_pk_bf16_f32 v73, v127, v129
	v_cvt_pk_bf16_f32 v66, v142, v175
	v_cvt_pk_bf16_f32 v67, v173, v178
	v_cvt_pk_bf16_f32 v68, v179, v182
	s_waitcnt lgkmcnt(0)
	v_mfma_f32_32x32x16_bf16 v[50:65], v[82:85], v[74:77], v[50:65]
	ds_read_b64_tr_b16 v[74:75], v0 offset:4096
	ds_read_b64_tr_b16 v[76:77], v86 offset:4096
	v_cvt_pk_bf16_f32 v69, v192, v193
	s_mov_b64 s[8:9], -1
	s_waitcnt lgkmcnt(0)
	v_mfma_f32_32x32x16_bf16 v[2:17], v[74:77], v[78:81], v[2:17]
	ds_read_b64_tr_b16 v[74:75], v87 offset:4096
	ds_read_b64_tr_b16 v[76:77], v88 offset:4096
	s_waitcnt lgkmcnt(0)
	v_mfma_f32_32x32x16_bf16 v[18:33], v[74:77], v[78:81], v[18:33]
	ds_read_b64_tr_b16 v[74:75], v89 offset:4096
	ds_read_b64_tr_b16 v[76:77], v90 offset:4096
	s_waitcnt lgkmcnt(0)
	v_mfma_f32_32x32x16_bf16 v[34:49], v[74:77], v[78:81], v[34:49]
	ds_read_b64_tr_b16 v[74:75], v91 offset:4096
	ds_read_b64_tr_b16 v[76:77], v92 offset:4096
	s_waitcnt lgkmcnt(0)
	v_mfma_f32_32x32x16_bf16 v[50:65], v[74:77], v[78:81], v[50:65]
	ds_read_b64_tr_b16 v[74:75], v0 offset:8192
	ds_read_b64_tr_b16 v[76:77], v86 offset:8192
	s_waitcnt lgkmcnt(0)
	v_mfma_f32_32x32x16_bf16 v[2:17], v[74:77], v[70:73], v[2:17]
	ds_read_b64_tr_b16 v[74:75], v87 offset:8192
	ds_read_b64_tr_b16 v[76:77], v88 offset:8192
	s_waitcnt lgkmcnt(0)
	v_mfma_f32_32x32x16_bf16 v[18:33], v[74:77], v[70:73], v[18:33]
	ds_read_b64_tr_b16 v[74:75], v89 offset:8192
	ds_read_b64_tr_b16 v[76:77], v90 offset:8192
	s_waitcnt lgkmcnt(0)
	v_mfma_f32_32x32x16_bf16 v[34:49], v[74:77], v[70:73], v[34:49]
	ds_read_b64_tr_b16 v[74:75], v91 offset:8192
	ds_read_b64_tr_b16 v[76:77], v92 offset:8192
	s_waitcnt lgkmcnt(0)
	v_mfma_f32_32x32x16_bf16 v[50:65], v[74:77], v[70:73], v[50:65]
	ds_read_b64_tr_b16 v[70:71], v0 offset:12288
	ds_read_b64_tr_b16 v[72:73], v86 offset:12288
	v_add_f32_e32 v0, 0, v128
	v_add_f32_e32 v0, v172, v0
	v_add_f32_e32 v0, v177, v0
	v_add_f32_e32 v0, v181, v0
	v_add_f32_e32 v0, v184, v0
	v_add_f32_e32 v0, v186, v0
	s_waitcnt lgkmcnt(0)
	v_mfma_f32_32x32x16_bf16 v[2:17], v[70:73], v[66:69], v[2:17]
	ds_read_b64_tr_b16 v[70:71], v87 offset:12288
	ds_read_b64_tr_b16 v[72:73], v88 offset:12288
	v_add_f32_e32 v0, v187, v0
	v_add_f32_e32 v0, v190, v0
	v_add_f32_e32 v0, v121, v0
	v_add_f32_e32 v0, v123, v0
	v_add_f32_e32 v0, v125, v0
	v_add_f32_e32 v0, v127, v0
	s_waitcnt lgkmcnt(0)
	v_mfma_f32_32x32x16_bf16 v[18:33], v[70:73], v[66:69], v[18:33]
	ds_read_b64_tr_b16 v[70:71], v89 offset:12288
	ds_read_b64_tr_b16 v[72:73], v90 offset:12288
	v_add_f32_e32 v0, v142, v0
	v_add_f32_e32 v0, v173, v0
	v_add_f32_e32 v0, v179, v0
	v_add_f32_e32 v0, v192, v0
	s_waitcnt lgkmcnt(0)
	v_mfma_f32_32x32x16_bf16 v[34:49], v[70:73], v[66:69], v[34:49]
	ds_read_b64_tr_b16 v[70:71], v91 offset:12288
	ds_read_b64_tr_b16 v[72:73], v92 offset:12288
	s_waitcnt vmcnt(0) lgkmcnt(0)
	s_barrier
	s_waitcnt lgkmcnt(0)
	v_mfma_f32_32x32x16_bf16 v[50:65], v[70:73], v[66:69], v[50:65]
	v_add_f32_e32 v66, 0, v174
	v_add_f32_e32 v66, v176, v66
	v_add_f32_e32 v66, v180, v66
	v_add_f32_e32 v66, v183, v66
	v_add_f32_e32 v66, v185, v66
	v_add_f32_e32 v66, v188, v66
	v_add_f32_e32 v66, v189, v66
	v_add_f32_e32 v66, v191, v66
	v_add_f32_e32 v66, v122, v66
	v_add_f32_e32 v66, v124, v66
	v_add_f32_e32 v66, v126, v66
	v_add_f32_e32 v66, v129, v66
	v_add_f32_e32 v66, v175, v66
	v_add_f32_e32 v66, v178, v66
	v_add_f32_e32 v66, v182, v66
	v_add_f32_e32 v66, v193, v66
	v_add_f32_e32 v0, v0, v66
	v_add_f32_e32 v0, v118, v0
	ds_bpermute_b32 v66, v143, v0
	s_waitcnt lgkmcnt(0)
	v_add_f32_e32 v0, v0, v66
	v_div_scale_f32 v66, s[2:3], v0, v0, 1.0
	v_rcp_f32_e32 v67, v66
	s_nop 0
	v_fma_f32 v68, -v66, v67, 1.0
	v_fmac_f32_e32 v67, v68, v67
	v_div_scale_f32 v68, vcc, 1.0, v0, 1.0
	v_mul_f32_e32 v69, v68, v67
	v_fma_f32 v70, -v66, v69, v68
	v_fmac_f32_e32 v69, v70, v67
	v_fma_f32 v66, -v66, v69, v68
	v_div_fmas_f32 v66, v66, v67, v69
	v_div_fixup_f32 v0, v66, v0, 1.0
	v_mov_b32_e32 v66, v140
	s_and_b64 vcc, exec, s[30:31]
	v_ashrrev_i32_e32 v67, 31, v66
	v_lshlrev_b64 v[66:67], 8, v[66:67]
	v_lshl_add_u64 v[132:133], s[86:87], 0, v[66:67]
	s_cbranch_vccnz .LBB0_288
	s_andn2_b64 vcc, exec, s[8:9]
	s_cbranch_vccnz .LBB0_219
	s_branch .LBB0_289
